# GEMM K-loop load segments: LDS-DMA staging issued before the fragment ds_reads (pure reordering inside barrier-delimited segments)
# baseline (speedup 1.0000x reference)
.LBB0_454:
	s_add_u32 s0, s2, 0xfffc0080
	s_addc_u32 s1, s3, -1
	s_add_i32 s9, 0, 0x10000
	s_cmp_eq_u32 s8, 12
	s_cselect_b32 s5, s47, s1
	s_cselect_b32 s4, s46, s0
	s_cselect_b32 s1, s49, s7
	s_cselect_b32 s0, s48, s6
	s_add_i32 s33, 0, 0x14000
	v_add_u32_e32 v140, s9, v166
	v_add_u32_e32 v168, s33, v166
	v_lshl_add_u64 v[200:201], s[2:3], 0, v[158:159]
	s_add_i32 m0, s21, 0xc000
	global_load_lds_dwordx4 v[200:201], off
	v_lshl_add_u64 v[200:201], s[2:3], 0, v[160:161]
	s_add_i32 m0, s21, 0xe000
	s_nop 0
	global_load_lds_dwordx4 v[200:201], off
	ds_read_b128 v[112:115], v140
	ds_read_b128 v[132:135], v140 offset:1024
	ds_read_b128 v[136:139], v140 offset:2048
	ds_read_b128 v[140:143], v140 offset:3072
	ds_read_b128 v[144:147], v168
	ds_read_b128 v[148:151], v168 offset:1024
	ds_read_b128 v[162:165], v168 offset:2048
	ds_read_b128 v[168:171], v168 offset:3072
	ds_read_b128 v[172:175], v167
	ds_read_b128 v[184:187], v167 offset:1024
	ds_read_b128 v[188:191], v167 offset:2048
	ds_read_b128 v[192:195], v167 offset:3072
	ds_read_b128 v[196:199], v167 offset:4096
	ds_read_b128 v[214:217], v167 offset:5120
	ds_read_b128 v[218:221], v167 offset:6144
	ds_read_b128 v[222:225], v167 offset:7168
	s_waitcnt vmcnt(8)
	s_waitcnt lgkmcnt(0)
	s_barrier
	s_setprio 1
	s_waitcnt lgkmcnt(0)
	v_mfma_f32_16x16x32_bf16 v[128:131], v[112:115], v[172:175], v[128:131]
	v_mfma_f32_16x16x32_bf16 v[124:127], v[136:139], v[172:175], v[124:127]
	v_mfma_f32_16x16x32_bf16 v[108:111], v[112:115], v[188:191], v[108:111]
	v_mfma_f32_16x16x32_bf16 v[104:107], v[136:139], v[188:191], v[104:107]
	v_mfma_f32_16x16x32_bf16 v[92:95], v[112:115], v[196:199], v[92:95]
	v_mfma_f32_16x16x32_bf16 v[88:91], v[136:139], v[196:199], v[88:91]
	v_mfma_f32_16x16x32_bf16 v[76:79], v[112:115], v[218:221], v[76:79]
	v_mfma_f32_16x16x32_bf16 v[72:75], v[136:139], v[218:221], v[72:75]
	v_mfma_f32_16x16x32_bf16 v[128:131], v[132:135], v[184:187], v[128:131]
	v_mfma_f32_16x16x32_bf16 v[124:127], v[140:143], v[184:187], v[124:127]
	v_mfma_f32_16x16x32_bf16 v[108:111], v[132:135], v[192:195], v[108:111]
	v_mfma_f32_16x16x32_bf16 v[104:107], v[140:143], v[192:195], v[104:107]
	v_mfma_f32_16x16x32_bf16 v[92:95], v[132:135], v[214:217], v[92:95]
	v_mfma_f32_16x16x32_bf16 v[88:91], v[140:143], v[214:217], v[88:91]
	v_mfma_f32_16x16x32_bf16 v[76:79], v[132:135], v[222:225], v[76:79]
	v_mfma_f32_16x16x32_bf16 v[72:75], v[140:143], v[222:225], v[72:75]
	s_setprio 0
	s_setprio 1
	v_mfma_f32_16x16x32_bf16 v[120:123], v[144:147], v[172:175], v[120:123]
	v_mfma_f32_16x16x32_bf16 v[116:119], v[162:165], v[172:175], v[116:119]
	v_mfma_f32_16x16x32_bf16 v[100:103], v[144:147], v[188:191], v[100:103]
	v_mfma_f32_16x16x32_bf16 v[96:99], v[162:165], v[188:191], v[96:99]
	v_mfma_f32_16x16x32_bf16 v[84:87], v[144:147], v[196:199], v[84:87]
	v_mfma_f32_16x16x32_bf16 v[80:83], v[162:165], v[196:199], v[80:83]
	v_mfma_f32_16x16x32_bf16 v[68:71], v[144:147], v[218:221], v[68:71]
	v_mfma_f32_16x16x32_bf16 v[64:67], v[162:165], v[218:221], v[64:67]
	v_mfma_f32_16x16x32_bf16 v[120:123], v[148:151], v[184:187], v[120:123]
	v_mfma_f32_16x16x32_bf16 v[116:119], v[168:171], v[184:187], v[116:119]
	v_mfma_f32_16x16x32_bf16 v[100:103], v[148:151], v[192:195], v[100:103]
	v_mfma_f32_16x16x32_bf16 v[96:99], v[168:171], v[192:195], v[96:99]
	v_mfma_f32_16x16x32_bf16 v[84:87], v[148:151], v[214:217], v[84:87]
	v_mfma_f32_16x16x32_bf16 v[80:83], v[168:171], v[214:217], v[80:83]
	v_mfma_f32_16x16x32_bf16 v[68:71], v[148:151], v[222:225], v[68:71]
	v_mfma_f32_16x16x32_bf16 v[64:67], v[168:171], v[222:225], v[64:67]
	s_setprio 0
	s_barrier
	s_add_i32 s9, s9, s13
	v_lshl_add_u64 v[200:201], s[0:1], 0, v[176:177]
	s_mov_b32 m0, s9
	global_load_lds_dwordx4 v[200:201], off
	s_add_i32 m0, s9, 0x2000
	s_add_u32 s36, s0, 0x40000
	v_lshl_add_u64 v[226:227], s[0:1], 0, v[156:157]
	s_addc_u32 s37, s1, 0
	s_add_i32 s9, s33, s13
	global_load_lds_dwordx4 v[226:227], off
	v_lshl_add_u64 v[228:229], s[36:37], 0, v[176:177]
	s_mov_b32 m0, s9
	v_lshl_add_u64 v[230:231], s[4:5], 0, v[154:155]
	global_load_lds_dwordx4 v[228:229], off
	v_lshl_add_u64 v[228:229], s[36:37], 0, v[156:157]
	s_add_i32 m0, s9, 0x2000
	s_nop 0
	global_load_lds_dwordx4 v[228:229], off
	v_lshl_add_u64 v[228:229], s[4:5], 0, v[152:153]
	s_mov_b32 m0, s21
	s_nop 0
	global_load_lds_dwordx4 v[228:229], off
	s_mov_b32 m0, s23
	s_nop 0
	global_load_lds_dwordx4 v[230:231], off
	ds_read_b128 v[172:175], v167 offset:16384
	ds_read_b128 v[184:187], v167 offset:17408
	ds_read_b128 v[188:191], v167 offset:18432
	ds_read_b128 v[192:195], v167 offset:19456
	ds_read_b128 v[196:199], v167 offset:20480
	ds_read_b128 v[214:217], v167 offset:21504
	ds_read_b128 v[218:221], v167 offset:22528
	ds_read_b128 v[222:225], v167 offset:23552
	s_waitcnt vmcnt(8)
	s_waitcnt lgkmcnt(0)
	s_barrier
	s_setprio 1
	s_waitcnt lgkmcnt(0)
	v_mfma_f32_16x16x32_bf16 v[60:63], v[112:115], v[172:175], v[60:63]
	v_mfma_f32_16x16x32_bf16 v[56:59], v[136:139], v[172:175], v[56:59]
	v_mfma_f32_16x16x32_bf16 v[44:47], v[112:115], v[188:191], v[44:47]
	v_mfma_f32_16x16x32_bf16 v[40:43], v[136:139], v[188:191], v[40:43]
	v_mfma_f32_16x16x32_bf16 v[28:31], v[112:115], v[196:199], v[28:31]
	v_mfma_f32_16x16x32_bf16 v[24:27], v[136:139], v[196:199], v[24:27]
	v_mfma_f32_16x16x32_bf16 v[12:15], v[112:115], v[218:221], v[12:15]
	v_mfma_f32_16x16x32_bf16 v[8:11], v[136:139], v[218:221], v[8:11]
	v_mfma_f32_16x16x32_bf16 v[60:63], v[132:135], v[184:187], v[60:63]
	v_mfma_f32_16x16x32_bf16 v[56:59], v[140:143], v[184:187], v[56:59]
	v_mfma_f32_16x16x32_bf16 v[44:47], v[132:135], v[192:195], v[44:47]
	v_mfma_f32_16x16x32_bf16 v[40:43], v[140:143], v[192:195], v[40:43]
	v_mfma_f32_16x16x32_bf16 v[28:31], v[132:135], v[214:217], v[28:31]
	v_mfma_f32_16x16x32_bf16 v[24:27], v[140:143], v[214:217], v[24:27]
	v_mfma_f32_16x16x32_bf16 v[12:15], v[132:135], v[222:225], v[12:15]
	v_mfma_f32_16x16x32_bf16 v[8:11], v[140:143], v[222:225], v[8:11]
	s_setprio 0
	s_setprio 1
	v_mfma_f32_16x16x32_bf16 v[52:55], v[144:147], v[172:175], v[52:55]
	v_mfma_f32_16x16x32_bf16 v[48:51], v[162:165], v[172:175], v[48:51]
	v_mfma_f32_16x16x32_bf16 v[36:39], v[144:147], v[188:191], v[36:39]
	v_mfma_f32_16x16x32_bf16 v[32:35], v[162:165], v[188:191], v[32:35]
	v_mfma_f32_16x16x32_bf16 v[20:23], v[144:147], v[196:199], v[20:23]
	v_mfma_f32_16x16x32_bf16 v[16:19], v[162:165], v[196:199], v[16:19]
	v_mfma_f32_16x16x32_bf16 v[4:7], v[144:147], v[218:221], v[4:7]
	v_mfma_f32_16x16x32_bf16 v[0:3], v[162:165], v[218:221], v[0:3]
	v_mfma_f32_16x16x32_bf16 v[52:55], v[148:151], v[184:187], v[52:55]
	v_mfma_f32_16x16x32_bf16 v[48:51], v[168:171], v[184:187], v[48:51]
	v_mfma_f32_16x16x32_bf16 v[36:39], v[148:151], v[192:195], v[36:39]
	v_mfma_f32_16x16x32_bf16 v[32:35], v[168:171], v[192:195], v[32:35]
	v_mfma_f32_16x16x32_bf16 v[20:23], v[148:151], v[214:217], v[20:23]
	v_mfma_f32_16x16x32_bf16 v[16:19], v[168:171], v[214:217], v[16:19]
	v_mfma_f32_16x16x32_bf16 v[4:7], v[148:151], v[222:225], v[4:7]
	v_mfma_f32_16x16x32_bf16 v[0:3], v[168:171], v[222:225], v[0:3]
	s_setprio 0
	s_barrier
	s_add_i32 s9, 0, 0x18000
	s_add_i32 s33, 0, 0x1c000
	v_add_u32_e32 v140, s9, v166
	v_add_u32_e32 v168, s33, v166
	s_add_u32 s4, s4, 0x40000
	s_addc_u32 s5, s5, 0
	s_mov_b32 m0, s52
	v_lshl_add_u64 v[232:233], s[4:5], 0, v[152:153]
	global_load_lds_dwordx4 v[232:233], off
	v_lshl_add_u64 v[232:233], s[4:5], 0, v[154:155]
	s_mov_b32 m0, s53
	s_nop 0
	global_load_lds_dwordx4 v[232:233], off
	ds_read_b128 v[112:115], v140
	ds_read_b128 v[132:135], v140 offset:1024
	ds_read_b128 v[136:139], v140 offset:2048
	ds_read_b128 v[140:143], v140 offset:3072
	ds_read_b128 v[144:147], v168
	ds_read_b128 v[148:151], v168 offset:1024
	ds_read_b128 v[162:165], v168 offset:2048
	ds_read_b128 v[168:171], v168 offset:3072
	ds_read_b128 v[172:175], v167 offset:32768
	ds_read_b128 v[184:187], v167 offset:33792
	ds_read_b128 v[188:191], v167 offset:34816
	ds_read_b128 v[192:195], v167 offset:35840
	ds_read_b128 v[196:199], v167 offset:36864
	ds_read_b128 v[214:217], v167 offset:37888
	ds_read_b128 v[218:221], v167 offset:38912
	ds_read_b128 v[222:225], v167 offset:39936
	s_waitcnt vmcnt(8)
	s_waitcnt lgkmcnt(0)
	s_barrier
	s_setprio 1
	s_waitcnt lgkmcnt(0)
	v_mfma_f32_16x16x32_bf16 v[128:131], v[112:115], v[172:175], v[128:131]
	v_mfma_f32_16x16x32_bf16 v[124:127], v[136:139], v[172:175], v[124:127]
	v_mfma_f32_16x16x32_bf16 v[108:111], v[112:115], v[188:191], v[108:111]
	v_mfma_f32_16x16x32_bf16 v[104:107], v[136:139], v[188:191], v[104:107]
	v_mfma_f32_16x16x32_bf16 v[92:95], v[112:115], v[196:199], v[92:95]
	v_mfma_f32_16x16x32_bf16 v[88:91], v[136:139], v[196:199], v[88:91]
	v_mfma_f32_16x16x32_bf16 v[76:79], v[112:115], v[218:221], v[76:79]
	v_mfma_f32_16x16x32_bf16 v[72:75], v[136:139], v[218:221], v[72:75]
	v_mfma_f32_16x16x32_bf16 v[128:131], v[132:135], v[184:187], v[128:131]
	v_mfma_f32_16x16x32_bf16 v[124:127], v[140:143], v[184:187], v[124:127]
	v_mfma_f32_16x16x32_bf16 v[108:111], v[132:135], v[192:195], v[108:111]
	v_mfma_f32_16x16x32_bf16 v[104:107], v[140:143], v[192:195], v[104:107]
	v_mfma_f32_16x16x32_bf16 v[92:95], v[132:135], v[214:217], v[92:95]
	v_mfma_f32_16x16x32_bf16 v[88:91], v[140:143], v[214:217], v[88:91]
	v_mfma_f32_16x16x32_bf16 v[76:79], v[132:135], v[222:225], v[76:79]
	v_mfma_f32_16x16x32_bf16 v[72:75], v[140:143], v[222:225], v[72:75]
	s_setprio 0
	s_setprio 1
	v_mfma_f32_16x16x32_bf16 v[120:123], v[144:147], v[172:175], v[120:123]
	v_mfma_f32_16x16x32_bf16 v[116:119], v[162:165], v[172:175], v[116:119]
	v_mfma_f32_16x16x32_bf16 v[100:103], v[144:147], v[188:191], v[100:103]
	v_mfma_f32_16x16x32_bf16 v[96:99], v[162:165], v[188:191], v[96:99]
	v_mfma_f32_16x16x32_bf16 v[84:87], v[144:147], v[196:199], v[84:87]
	v_mfma_f32_16x16x32_bf16 v[80:83], v[162:165], v[196:199], v[80:83]
	v_mfma_f32_16x16x32_bf16 v[68:71], v[144:147], v[218:221], v[68:71]
	v_mfma_f32_16x16x32_bf16 v[64:67], v[162:165], v[218:221], v[64:67]
	v_mfma_f32_16x16x32_bf16 v[120:123], v[148:151], v[184:187], v[120:123]
	v_mfma_f32_16x16x32_bf16 v[116:119], v[168:171], v[184:187], v[116:119]
	v_mfma_f32_16x16x32_bf16 v[100:103], v[148:151], v[192:195], v[100:103]
	v_mfma_f32_16x16x32_bf16 v[96:99], v[168:171], v[192:195], v[96:99]
	v_mfma_f32_16x16x32_bf16 v[84:87], v[148:151], v[214:217], v[84:87]
	v_mfma_f32_16x16x32_bf16 v[80:83], v[168:171], v[214:217], v[80:83]
	v_mfma_f32_16x16x32_bf16 v[68:71], v[148:151], v[222:225], v[68:71]
	v_mfma_f32_16x16x32_bf16 v[64:67], v[168:171], v[222:225], v[64:67]
	s_setprio 0
	s_barrier
	s_add_i32 s4, s9, s13
	v_lshl_add_u64 v[200:201], v[200:201], 0, s[58:59]
	s_mov_b32 m0, s4
	global_load_lds_dwordx4 v[200:201], off
	s_add_i32 m0, s4, 0x2000
	s_add_u32 s0, s0, 0x40080
	v_lshl_add_u64 v[200:201], v[226:227], 0, s[58:59]
	s_addc_u32 s1, s1, 0
	s_add_i32 s4, s33, s13
	global_load_lds_dwordx4 v[200:201], off
	v_lshl_add_u64 v[200:201], s[0:1], 0, v[176:177]
	s_mov_b32 m0, s4
	s_nop 0
	global_load_lds_dwordx4 v[200:201], off
	v_lshl_add_u64 v[200:201], s[0:1], 0, v[156:157]
	s_add_i32 m0, s4, 0x2000
	s_nop 0
	global_load_lds_dwordx4 v[200:201], off
	v_lshl_add_u64 v[200:201], v[228:229], 0, s[58:59]
	s_mov_b32 m0, s79
	s_nop 0
	global_load_lds_dwordx4 v[200:201], off
	v_lshl_add_u64 v[200:201], v[230:231], 0, s[58:59]
	s_mov_b32 m0, s80
	s_nop 0
	global_load_lds_dwordx4 v[200:201], off
	ds_read_b128 v[172:175], v167 offset:49152
	ds_read_b128 v[184:187], v167 offset:50176
	ds_read_b128 v[188:191], v167 offset:51200
	ds_read_b128 v[192:195], v167 offset:52224
	ds_read_b128 v[196:199], v167 offset:53248
	ds_read_b128 v[214:217], v167 offset:54272
	ds_read_b128 v[218:221], v167 offset:55296
	ds_read_b128 v[222:225], v167 offset:56320
	s_waitcnt vmcnt(8)
	s_waitcnt lgkmcnt(0)
	s_barrier
	s_setprio 1
	s_waitcnt lgkmcnt(0)
	v_mfma_f32_16x16x32_bf16 v[60:63], v[112:115], v[172:175], v[60:63]
	v_mfma_f32_16x16x32_bf16 v[56:59], v[136:139], v[172:175], v[56:59]
	v_mfma_f32_16x16x32_bf16 v[44:47], v[112:115], v[188:191], v[44:47]
	v_mfma_f32_16x16x32_bf16 v[40:43], v[136:139], v[188:191], v[40:43]
	v_mfma_f32_16x16x32_bf16 v[28:31], v[112:115], v[196:199], v[28:31]
	v_mfma_f32_16x16x32_bf16 v[24:27], v[136:139], v[196:199], v[24:27]
	v_mfma_f32_16x16x32_bf16 v[12:15], v[112:115], v[218:221], v[12:15]
	v_mfma_f32_16x16x32_bf16 v[8:11], v[136:139], v[218:221], v[8:11]
	v_mfma_f32_16x16x32_bf16 v[60:63], v[132:135], v[184:187], v[60:63]
	v_mfma_f32_16x16x32_bf16 v[56:59], v[140:143], v[184:187], v[56:59]
	v_mfma_f32_16x16x32_bf16 v[44:47], v[132:135], v[192:195], v[44:47]
	v_mfma_f32_16x16x32_bf16 v[40:43], v[140:143], v[192:195], v[40:43]
	v_mfma_f32_16x16x32_bf16 v[28:31], v[132:135], v[214:217], v[28:31]
	v_mfma_f32_16x16x32_bf16 v[24:27], v[140:143], v[214:217], v[24:27]
	v_mfma_f32_16x16x32_bf16 v[12:15], v[132:135], v[222:225], v[12:15]
	v_mfma_f32_16x16x32_bf16 v[8:11], v[140:143], v[222:225], v[8:11]
	s_setprio 0
	s_setprio 1
	v_mfma_f32_16x16x32_bf16 v[52:55], v[144:147], v[172:175], v[52:55]
	v_mfma_f32_16x16x32_bf16 v[48:51], v[162:165], v[172:175], v[48:51]
	v_mfma_f32_16x16x32_bf16 v[36:39], v[144:147], v[188:191], v[36:39]
	v_mfma_f32_16x16x32_bf16 v[32:35], v[162:165], v[188:191], v[32:35]
	v_mfma_f32_16x16x32_bf16 v[20:23], v[144:147], v[196:199], v[20:23]
	v_mfma_f32_16x16x32_bf16 v[16:19], v[162:165], v[196:199], v[16:19]
	v_mfma_f32_16x16x32_bf16 v[4:7], v[144:147], v[218:221], v[4:7]
	v_mfma_f32_16x16x32_bf16 v[0:3], v[162:165], v[218:221], v[0:3]
	v_mfma_f32_16x16x32_bf16 v[52:55], v[148:151], v[184:187], v[52:55]
	v_mfma_f32_16x16x32_bf16 v[48:51], v[168:171], v[184:187], v[48:51]
	v_mfma_f32_16x16x32_bf16 v[36:39], v[148:151], v[192:195], v[36:39]
	v_mfma_f32_16x16x32_bf16 v[32:35], v[168:171], v[192:195], v[32:35]
	v_mfma_f32_16x16x32_bf16 v[20:23], v[148:151], v[214:217], v[20:23]
	v_mfma_f32_16x16x32_bf16 v[16:19], v[168:171], v[214:217], v[16:19]
	v_mfma_f32_16x16x32_bf16 v[4:7], v[148:151], v[222:225], v[4:7]
	v_mfma_f32_16x16x32_bf16 v[0:3], v[168:171], v[222:225], v[0:3]
	s_setprio 0
	s_barrier
	s_add_i32 s8, s8, 2
	s_add_u32 s2, s2, 0x100
	s_addc_u32 s3, s3, 0
	s_add_u32 s6, s6, 0x100
	s_addc_u32 s7, s7, 0
	s_cmp_gt_u32 s8, 13
	s_cbranch_scc0 .LBB0_454
	s_and_b64 vcc, exec, s[34:35]
	s_cbranch_vccz .LBB0_457
	s_barrier

.LBB0_527:
	s_add_u32 s4, s36, 0xfffc0080
	s_addc_u32 s5, s37, -1
	s_add_i32 s47, 0, 0x10000
	s_cmp_eq_u32 s46, 12
	s_cselect_b32 s5, s1, s5
	s_cselect_b32 s4, s0, s4
	v_add_u32_e32 v151, s47, v149
	s_cselect_b32 s49, s3, s33
	s_cselect_b32 s48, s2, s9
	s_add_i32 s54, 0, 0x14000
	ds_read_b128 v[128:131], v151
	ds_read_b128 v[144:147], v151 offset:1024
	ds_read_b128 v[152:155], v151 offset:2048
	ds_read_b128 v[156:159], v151 offset:3072
	v_add_u32_e32 v151, s54, v149
	ds_read_b128 v[160:163], v151
	ds_read_b128 v[164:167], v151 offset:1024
	ds_read_b128 v[168:171], v151 offset:2048
	ds_read_b128 v[172:175], v151 offset:3072
	v_lshl_add_u64 v[200:201], s[36:37], 0, v[140:141]
	s_add_i32 m0, s79, 0xc000
	ds_read_b128 v[184:187], v150
	ds_read_b128 v[188:191], v150 offset:1024
	ds_read_b128 v[192:195], v150 offset:2048
	ds_read_b128 v[196:199], v150 offset:3072
	ds_read_b128 v[214:217], v150 offset:4096
	ds_read_b128 v[218:221], v150 offset:5120
	ds_read_b128 v[222:225], v150 offset:6144
	ds_read_b128 v[226:229], v150 offset:7168
	global_load_lds_dwordx4 v[200:201], off
	v_lshl_add_u64 v[200:201], s[36:37], 0, v[142:143]
	s_add_i32 m0, s79, 0xe000
	s_nop 0
	global_load_lds_dwordx4 v[200:201], off
	s_waitcnt vmcnt(8)
	s_waitcnt lgkmcnt(0)
	s_barrier
	s_setprio 1
	s_waitcnt lgkmcnt(0)
	v_mfma_f32_16x16x32_bf16 v[124:127], v[128:131], v[184:187], v[124:127]
	v_mfma_f32_16x16x32_bf16 v[120:123], v[152:155], v[184:187], v[120:123]
	v_mfma_f32_16x16x32_bf16 v[116:119], v[128:131], v[192:195], v[116:119]
	v_mfma_f32_16x16x32_bf16 v[112:115], v[152:155], v[192:195], v[112:115]
	v_mfma_f32_16x16x32_bf16 v[108:111], v[128:131], v[214:217], v[108:111]
	v_mfma_f32_16x16x32_bf16 v[104:107], v[152:155], v[214:217], v[104:107]
	v_mfma_f32_16x16x32_bf16 v[100:103], v[128:131], v[222:225], v[100:103]
	v_mfma_f32_16x16x32_bf16 v[96:99], v[152:155], v[222:225], v[96:99]
	v_mfma_f32_16x16x32_bf16 v[124:127], v[144:147], v[188:191], v[124:127]
	v_mfma_f32_16x16x32_bf16 v[120:123], v[156:159], v[188:191], v[120:123]
	v_mfma_f32_16x16x32_bf16 v[116:119], v[144:147], v[196:199], v[116:119]
	v_mfma_f32_16x16x32_bf16 v[112:115], v[156:159], v[196:199], v[112:115]
	v_mfma_f32_16x16x32_bf16 v[108:111], v[144:147], v[218:221], v[108:111]
	v_mfma_f32_16x16x32_bf16 v[104:107], v[156:159], v[218:221], v[104:107]
	v_mfma_f32_16x16x32_bf16 v[100:103], v[144:147], v[226:229], v[100:103]
	v_mfma_f32_16x16x32_bf16 v[96:99], v[156:159], v[226:229], v[96:99]
	s_setprio 0
	s_setprio 1
	v_mfma_f32_16x16x32_bf16 v[60:63], v[160:163], v[184:187], v[60:63]
	v_mfma_f32_16x16x32_bf16 v[56:59], v[168:171], v[184:187], v[56:59]
	v_mfma_f32_16x16x32_bf16 v[52:55], v[160:163], v[192:195], v[52:55]
	v_mfma_f32_16x16x32_bf16 v[48:51], v[168:171], v[192:195], v[48:51]
	v_mfma_f32_16x16x32_bf16 v[44:47], v[160:163], v[214:217], v[44:47]
	v_mfma_f32_16x16x32_bf16 v[40:43], v[168:171], v[214:217], v[40:43]
	v_mfma_f32_16x16x32_bf16 v[36:39], v[160:163], v[222:225], v[36:39]
	v_mfma_f32_16x16x32_bf16 v[32:35], v[168:171], v[222:225], v[32:35]
	v_mfma_f32_16x16x32_bf16 v[60:63], v[164:167], v[188:191], v[60:63]
	v_mfma_f32_16x16x32_bf16 v[56:59], v[172:175], v[188:191], v[56:59]
	v_mfma_f32_16x16x32_bf16 v[52:55], v[164:167], v[196:199], v[52:55]
	v_mfma_f32_16x16x32_bf16 v[48:51], v[172:175], v[196:199], v[48:51]
	v_mfma_f32_16x16x32_bf16 v[44:47], v[164:167], v[218:221], v[44:47]
	v_mfma_f32_16x16x32_bf16 v[40:43], v[172:175], v[218:221], v[40:43]
	v_mfma_f32_16x16x32_bf16 v[36:39], v[164:167], v[226:229], v[36:39]
	v_mfma_f32_16x16x32_bf16 v[32:35], v[172:175], v[226:229], v[32:35]
	s_setprio 0
	s_barrier
	s_add_i32 s47, s47, s21
	v_lshl_add_u64 v[200:201], s[48:49], 0, v[134:135]
	s_mov_b32 m0, s47
	global_load_lds_dwordx4 v[200:201], off
	s_add_i32 m0, s47, 0x2000
	v_lshl_add_u64 v[230:231], s[48:49], 0, v[138:139]
	s_add_u32 s48, s48, s40
	s_addc_u32 s49, s49, s41
	s_add_i32 s47, s54, s21
	global_load_lds_dwordx4 v[230:231], off
	v_lshl_add_u64 v[232:233], s[48:49], 0, v[134:135]
	s_mov_b32 m0, s47
	v_lshl_add_u64 v[234:235], s[48:49], 0, v[138:139]
	global_load_lds_dwordx4 v[232:233], off
	s_add_i32 m0, s47, 0x2000
	v_lshl_add_u64 v[236:237], s[4:5], 0, v[132:133]
	global_load_lds_dwordx4 v[234:235], off
	s_mov_b32 m0, s79
	v_lshl_add_u64 v[238:239], s[4:5], 0, v[136:137]
	global_load_lds_dwordx4 v[236:237], off
	s_mov_b32 m0, s80
	s_nop 0
	global_load_lds_dwordx4 v[238:239], off
	ds_read_b128 v[184:187], v150 offset:16384
	ds_read_b128 v[188:191], v150 offset:17408
	ds_read_b128 v[192:195], v150 offset:18432
	ds_read_b128 v[196:199], v150 offset:19456
	ds_read_b128 v[214:217], v150 offset:20480
	ds_read_b128 v[218:221], v150 offset:21504
	ds_read_b128 v[222:225], v150 offset:22528
	ds_read_b128 v[226:229], v150 offset:23552
	s_waitcnt vmcnt(8)
	s_waitcnt lgkmcnt(0)
	s_barrier
	s_setprio 1
	s_waitcnt lgkmcnt(0)
	v_mfma_f32_16x16x32_bf16 v[92:95], v[128:131], v[184:187], v[92:95]
	v_mfma_f32_16x16x32_bf16 v[88:91], v[152:155], v[184:187], v[88:91]
	v_mfma_f32_16x16x32_bf16 v[84:87], v[128:131], v[192:195], v[84:87]
	v_mfma_f32_16x16x32_bf16 v[80:83], v[152:155], v[192:195], v[80:83]
	v_mfma_f32_16x16x32_bf16 v[76:79], v[128:131], v[214:217], v[76:79]
	v_mfma_f32_16x16x32_bf16 v[72:75], v[152:155], v[214:217], v[72:75]
	v_mfma_f32_16x16x32_bf16 v[68:71], v[128:131], v[222:225], v[68:71]
	v_mfma_f32_16x16x32_bf16 v[64:67], v[152:155], v[222:225], v[64:67]
	v_mfma_f32_16x16x32_bf16 v[92:95], v[144:147], v[188:191], v[92:95]
	v_mfma_f32_16x16x32_bf16 v[88:91], v[156:159], v[188:191], v[88:91]
	v_mfma_f32_16x16x32_bf16 v[84:87], v[144:147], v[196:199], v[84:87]
	v_mfma_f32_16x16x32_bf16 v[80:83], v[156:159], v[196:199], v[80:83]
	v_mfma_f32_16x16x32_bf16 v[76:79], v[144:147], v[218:221], v[76:79]
	v_mfma_f32_16x16x32_bf16 v[72:75], v[156:159], v[218:221], v[72:75]
	v_mfma_f32_16x16x32_bf16 v[68:71], v[144:147], v[226:229], v[68:71]
	v_mfma_f32_16x16x32_bf16 v[64:67], v[156:159], v[226:229], v[64:67]
	s_setprio 0
	s_setprio 1
	v_mfma_f32_16x16x32_bf16 v[28:31], v[160:163], v[184:187], v[28:31]
	v_mfma_f32_16x16x32_bf16 v[24:27], v[168:171], v[184:187], v[24:27]
	v_mfma_f32_16x16x32_bf16 v[20:23], v[160:163], v[192:195], v[20:23]
	v_mfma_f32_16x16x32_bf16 v[16:19], v[168:171], v[192:195], v[16:19]
	v_mfma_f32_16x16x32_bf16 v[12:15], v[160:163], v[214:217], v[12:15]
	v_mfma_f32_16x16x32_bf16 v[8:11], v[168:171], v[214:217], v[8:11]
	v_mfma_f32_16x16x32_bf16 v[4:7], v[160:163], v[222:225], v[4:7]
	v_mfma_f32_16x16x32_bf16 v[0:3], v[168:171], v[222:225], v[0:3]
	v_mfma_f32_16x16x32_bf16 v[28:31], v[164:167], v[188:191], v[28:31]
	v_mfma_f32_16x16x32_bf16 v[24:27], v[172:175], v[188:191], v[24:27]
	v_mfma_f32_16x16x32_bf16 v[20:23], v[164:167], v[196:199], v[20:23]
	v_mfma_f32_16x16x32_bf16 v[16:19], v[172:175], v[196:199], v[16:19]
	v_mfma_f32_16x16x32_bf16 v[12:15], v[164:167], v[218:221], v[12:15]
	v_mfma_f32_16x16x32_bf16 v[8:11], v[172:175], v[218:221], v[8:11]
	v_mfma_f32_16x16x32_bf16 v[4:7], v[164:167], v[226:229], v[4:7]
	v_mfma_f32_16x16x32_bf16 v[0:3], v[172:175], v[226:229], v[0:3]
	s_setprio 0
	s_barrier
	s_add_i32 s47, 0, 0x18000
	v_add_u32_e32 v151, s47, v149
	s_add_i32 s48, 0, 0x1c000
	ds_read_b128 v[128:131], v151
	ds_read_b128 v[144:147], v151 offset:1024
	ds_read_b128 v[152:155], v151 offset:2048
	ds_read_b128 v[156:159], v151 offset:3072
	v_add_u32_e32 v151, s48, v149
	ds_read_b128 v[160:163], v151
	ds_read_b128 v[164:167], v151 offset:1024
	ds_read_b128 v[168:171], v151 offset:2048
	ds_read_b128 v[172:175], v151 offset:3072
	s_add_u32 s4, s4, 0x40000
	s_addc_u32 s5, s5, 0
	s_mov_b32 m0, s81
	v_lshl_add_u64 v[240:241], s[4:5], 0, v[132:133]
	ds_read_b128 v[184:187], v150 offset:32768
	ds_read_b128 v[188:191], v150 offset:33792
	ds_read_b128 v[192:195], v150 offset:34816
	ds_read_b128 v[196:199], v150 offset:35840
	ds_read_b128 v[214:217], v150 offset:36864
	ds_read_b128 v[218:221], v150 offset:37888
	ds_read_b128 v[222:225], v150 offset:38912
	ds_read_b128 v[226:229], v150 offset:39936
	global_load_lds_dwordx4 v[240:241], off
	v_lshl_add_u64 v[240:241], s[4:5], 0, v[136:137]
	s_mov_b32 m0, s82
	s_nop 0
	global_load_lds_dwordx4 v[240:241], off
	s_waitcnt vmcnt(8)
	s_waitcnt lgkmcnt(0)
	s_barrier
	s_setprio 1
	s_waitcnt lgkmcnt(0)
	v_mfma_f32_16x16x32_bf16 v[124:127], v[128:131], v[184:187], v[124:127]
	v_mfma_f32_16x16x32_bf16 v[120:123], v[152:155], v[184:187], v[120:123]
	v_mfma_f32_16x16x32_bf16 v[116:119], v[128:131], v[192:195], v[116:119]
	v_mfma_f32_16x16x32_bf16 v[112:115], v[152:155], v[192:195], v[112:115]
	v_mfma_f32_16x16x32_bf16 v[108:111], v[128:131], v[214:217], v[108:111]
	v_mfma_f32_16x16x32_bf16 v[104:107], v[152:155], v[214:217], v[104:107]
	v_mfma_f32_16x16x32_bf16 v[100:103], v[128:131], v[222:225], v[100:103]
	v_mfma_f32_16x16x32_bf16 v[96:99], v[152:155], v[222:225], v[96:99]
	v_mfma_f32_16x16x32_bf16 v[124:127], v[144:147], v[188:191], v[124:127]
	v_mfma_f32_16x16x32_bf16 v[120:123], v[156:159], v[188:191], v[120:123]
	v_mfma_f32_16x16x32_bf16 v[116:119], v[144:147], v[196:199], v[116:119]
	v_mfma_f32_16x16x32_bf16 v[112:115], v[156:159], v[196:199], v[112:115]
	v_mfma_f32_16x16x32_bf16 v[108:111], v[144:147], v[218:221], v[108:111]
	v_mfma_f32_16x16x32_bf16 v[104:107], v[156:159], v[218:221], v[104:107]
	v_mfma_f32_16x16x32_bf16 v[100:103], v[144:147], v[226:229], v[100:103]
	v_mfma_f32_16x16x32_bf16 v[96:99], v[156:159], v[226:229], v[96:99]
	s_setprio 0
	s_setprio 1
	v_mfma_f32_16x16x32_bf16 v[60:63], v[160:163], v[184:187], v[60:63]
	v_mfma_f32_16x16x32_bf16 v[56:59], v[168:171], v[184:187], v[56:59]
	v_mfma_f32_16x16x32_bf16 v[52:55], v[160:163], v[192:195], v[52:55]
	v_mfma_f32_16x16x32_bf16 v[48:51], v[168:171], v[192:195], v[48:51]
	v_mfma_f32_16x16x32_bf16 v[44:47], v[160:163], v[214:217], v[44:47]
	v_mfma_f32_16x16x32_bf16 v[40:43], v[168:171], v[214:217], v[40:43]
	v_mfma_f32_16x16x32_bf16 v[36:39], v[160:163], v[222:225], v[36:39]
	v_mfma_f32_16x16x32_bf16 v[32:35], v[168:171], v[222:225], v[32:35]
	v_mfma_f32_16x16x32_bf16 v[60:63], v[164:167], v[188:191], v[60:63]
	v_mfma_f32_16x16x32_bf16 v[56:59], v[172:175], v[188:191], v[56:59]
	v_mfma_f32_16x16x32_bf16 v[52:55], v[164:167], v[196:199], v[52:55]
	v_mfma_f32_16x16x32_bf16 v[48:51], v[172:175], v[196:199], v[48:51]
	v_mfma_f32_16x16x32_bf16 v[44:47], v[164:167], v[218:221], v[44:47]
	v_mfma_f32_16x16x32_bf16 v[40:43], v[172:175], v[218:221], v[40:43]
	v_mfma_f32_16x16x32_bf16 v[36:39], v[164:167], v[226:229], v[36:39]
	v_mfma_f32_16x16x32_bf16 v[32:35], v[172:175], v[226:229], v[32:35]
	s_setprio 0
	s_barrier
	s_add_i32 s4, s47, s21
	v_lshl_add_u64 v[200:201], v[200:201], 0, s[58:59]
	s_mov_b32 m0, s4
	global_load_lds_dwordx4 v[200:201], off
	v_lshl_add_u64 v[200:201], v[230:231], 0, s[58:59]
	s_add_i32 m0, s4, 0x2000
	s_add_i32 s4, s48, s21
	global_load_lds_dwordx4 v[200:201], off
	v_lshl_add_u64 v[200:201], v[232:233], 0, s[58:59]
	s_mov_b32 m0, s4
	s_nop 0
	global_load_lds_dwordx4 v[200:201], off
	v_lshl_add_u64 v[200:201], v[234:235], 0, s[58:59]
	s_add_i32 m0, s4, 0x2000
	s_nop 0
	global_load_lds_dwordx4 v[200:201], off
	v_lshl_add_u64 v[200:201], v[236:237], 0, s[58:59]
	s_mov_b32 m0, s85
	s_nop 0
	global_load_lds_dwordx4 v[200:201], off
	v_lshl_add_u64 v[200:201], v[238:239], 0, s[58:59]
	s_mov_b32 m0, s86
	s_nop 0
	global_load_lds_dwordx4 v[200:201], off
	ds_read_b128 v[184:187], v150 offset:49152
	ds_read_b128 v[188:191], v150 offset:50176
	ds_read_b128 v[192:195], v150 offset:51200
	ds_read_b128 v[196:199], v150 offset:52224
	ds_read_b128 v[214:217], v150 offset:53248
	ds_read_b128 v[218:221], v150 offset:54272
	ds_read_b128 v[222:225], v150 offset:55296
	ds_read_b128 v[226:229], v150 offset:56320
	s_waitcnt vmcnt(8)
	s_waitcnt lgkmcnt(0)
	s_barrier
	s_setprio 1
	s_waitcnt lgkmcnt(0)
	v_mfma_f32_16x16x32_bf16 v[92:95], v[128:131], v[184:187], v[92:95]
	v_mfma_f32_16x16x32_bf16 v[88:91], v[152:155], v[184:187], v[88:91]
	v_mfma_f32_16x16x32_bf16 v[84:87], v[128:131], v[192:195], v[84:87]
	v_mfma_f32_16x16x32_bf16 v[80:83], v[152:155], v[192:195], v[80:83]
	v_mfma_f32_16x16x32_bf16 v[76:79], v[128:131], v[214:217], v[76:79]
	v_mfma_f32_16x16x32_bf16 v[72:75], v[152:155], v[214:217], v[72:75]
	v_mfma_f32_16x16x32_bf16 v[68:71], v[128:131], v[222:225], v[68:71]
	v_mfma_f32_16x16x32_bf16 v[64:67], v[152:155], v[222:225], v[64:67]
	v_mfma_f32_16x16x32_bf16 v[92:95], v[144:147], v[188:191], v[92:95]
	v_mfma_f32_16x16x32_bf16 v[88:91], v[156:159], v[188:191], v[88:91]
	v_mfma_f32_16x16x32_bf16 v[84:87], v[144:147], v[196:199], v[84:87]
	v_mfma_f32_16x16x32_bf16 v[80:83], v[156:159], v[196:199], v[80:83]
	v_mfma_f32_16x16x32_bf16 v[76:79], v[144:147], v[218:221], v[76:79]
	v_mfma_f32_16x16x32_bf16 v[72:75], v[156:159], v[218:221], v[72:75]
	v_mfma_f32_16x16x32_bf16 v[68:71], v[144:147], v[226:229], v[68:71]
	v_mfma_f32_16x16x32_bf16 v[64:67], v[156:159], v[226:229], v[64:67]
	s_setprio 0
	s_setprio 1
	v_mfma_f32_16x16x32_bf16 v[28:31], v[160:163], v[184:187], v[28:31]
	v_mfma_f32_16x16x32_bf16 v[24:27], v[168:171], v[184:187], v[24:27]
	v_mfma_f32_16x16x32_bf16 v[20:23], v[160:163], v[192:195], v[20:23]
	v_mfma_f32_16x16x32_bf16 v[16:19], v[168:171], v[192:195], v[16:19]
	v_mfma_f32_16x16x32_bf16 v[12:15], v[160:163], v[214:217], v[12:15]
	v_mfma_f32_16x16x32_bf16 v[8:11], v[168:171], v[214:217], v[8:11]
	v_mfma_f32_16x16x32_bf16 v[4:7], v[160:163], v[222:225], v[4:7]
	v_mfma_f32_16x16x32_bf16 v[0:3], v[168:171], v[222:225], v[0:3]
	v_mfma_f32_16x16x32_bf16 v[28:31], v[164:167], v[188:191], v[28:31]
	v_mfma_f32_16x16x32_bf16 v[24:27], v[172:175], v[188:191], v[24:27]
	v_mfma_f32_16x16x32_bf16 v[20:23], v[164:167], v[196:199], v[20:23]
	v_mfma_f32_16x16x32_bf16 v[16:19], v[172:175], v[196:199], v[16:19]
	v_mfma_f32_16x16x32_bf16 v[12:15], v[164:167], v[218:221], v[12:15]
	v_mfma_f32_16x16x32_bf16 v[8:11], v[172:175], v[218:221], v[8:11]
	v_mfma_f32_16x16x32_bf16 v[4:7], v[164:167], v[226:229], v[4:7]
	v_mfma_f32_16x16x32_bf16 v[0:3], v[172:175], v[226:229], v[0:3]
	s_setprio 0
	s_barrier
	s_add_i32 s46, s46, 2
	s_add_u32 s36, s36, 0x100
	s_addc_u32 s37, s37, 0
	s_add_u32 s9, s9, 0x100
	s_addc_u32 s33, s33, 0
	s_cmp_gt_u32 s46, 13
	s_cbranch_scc0 .LBB0_527
	s_and_b64 vcc, exec, s[44:45]
	s_cbranch_vccz .LBB0_530
	s_barrier

.LBB0_582:
	s_add_u32 s50, s6, s48
	s_addc_u32 s51, s7, s49
	s_add_u32 s50, s50, 0x100
	s_addc_u32 s51, s51, 0
	s_add_u32 s57, s41, s48
	s_addc_u32 s58, s43, s49
	s_add_i32 s59, 0, 0x10000
	s_cmpk_eq_i32 s48, 0x700
	s_cselect_b32 s53, s45, s51
	s_cselect_b32 s52, s44, s50
	v_add_u32_e32 v156, s59, v161
	s_cselect_b32 s51, s47, s58
	s_cselect_b32 s50, s46, s57
	s_add_i32 s57, 0, 0x14000
	ds_read_b128 v[132:135], v156
	ds_read_b128 v[136:139], v156 offset:1024
	ds_read_b128 v[140:143], v156 offset:2048
	ds_read_b128 v[164:167], v156 offset:3072
	v_add_u32_e32 v156, s57, v161
	ds_read_b128 v[168:171], v156
	ds_read_b128 v[172:175], v156 offset:1024
	ds_read_b128 v[184:187], v156 offset:2048
	ds_read_b128 v[188:191], v156 offset:3072
	v_lshl_add_u64 v[156:157], v[130:131], 0, s[48:49]
	s_add_i32 m0, s33, 0xc000
	ds_read_b128 v[192:195], v163
	ds_read_b128 v[196:199], v163 offset:1024
	ds_read_b128 v[214:217], v163 offset:2048
	ds_read_b128 v[218:221], v163 offset:3072
	ds_read_b128 v[222:225], v163 offset:4096
	ds_read_b128 v[226:229], v163 offset:5120
	ds_read_b128 v[230:233], v163 offset:6144
	ds_read_b128 v[234:237], v163 offset:7168
	global_load_lds_dwordx4 v[156:157], off
	v_lshl_add_u64 v[156:157], v[128:129], 0, s[48:49]
	s_add_i32 m0, s33, 0xe000
	s_nop 0
	global_load_lds_dwordx4 v[156:157], off
	s_waitcnt vmcnt(8)
	s_waitcnt lgkmcnt(0)
	s_barrier
	s_setprio 1
	s_waitcnt lgkmcnt(0)
	v_mfma_f32_16x16x32_bf16 v[124:127], v[132:135], v[192:195], v[124:127]
	v_mfma_f32_16x16x32_bf16 v[120:123], v[140:143], v[192:195], v[120:123]
	v_mfma_f32_16x16x32_bf16 v[108:111], v[132:135], v[214:217], v[108:111]
	v_mfma_f32_16x16x32_bf16 v[104:107], v[140:143], v[214:217], v[104:107]
	v_mfma_f32_16x16x32_bf16 v[92:95], v[132:135], v[222:225], v[92:95]
	v_mfma_f32_16x16x32_bf16 v[88:91], v[140:143], v[222:225], v[88:91]
	v_mfma_f32_16x16x32_bf16 v[76:79], v[132:135], v[230:233], v[76:79]
	v_mfma_f32_16x16x32_bf16 v[72:75], v[140:143], v[230:233], v[72:75]
	v_mfma_f32_16x16x32_bf16 v[124:127], v[136:139], v[196:199], v[124:127]
	v_mfma_f32_16x16x32_bf16 v[120:123], v[164:167], v[196:199], v[120:123]
	v_mfma_f32_16x16x32_bf16 v[108:111], v[136:139], v[218:221], v[108:111]
	v_mfma_f32_16x16x32_bf16 v[104:107], v[164:167], v[218:221], v[104:107]
	v_mfma_f32_16x16x32_bf16 v[92:95], v[136:139], v[226:229], v[92:95]
	v_mfma_f32_16x16x32_bf16 v[88:91], v[164:167], v[226:229], v[88:91]
	v_mfma_f32_16x16x32_bf16 v[76:79], v[136:139], v[234:237], v[76:79]
	v_mfma_f32_16x16x32_bf16 v[72:75], v[164:167], v[234:237], v[72:75]
	s_setprio 0
	s_setprio 1
	v_mfma_f32_16x16x32_bf16 v[116:119], v[168:171], v[192:195], v[116:119]
	v_mfma_f32_16x16x32_bf16 v[112:115], v[184:187], v[192:195], v[112:115]
	v_mfma_f32_16x16x32_bf16 v[100:103], v[168:171], v[214:217], v[100:103]
	v_mfma_f32_16x16x32_bf16 v[96:99], v[184:187], v[214:217], v[96:99]
	v_mfma_f32_16x16x32_bf16 v[84:87], v[168:171], v[222:225], v[84:87]
	v_mfma_f32_16x16x32_bf16 v[80:83], v[184:187], v[222:225], v[80:83]
	v_mfma_f32_16x16x32_bf16 v[68:71], v[168:171], v[230:233], v[68:71]
	v_mfma_f32_16x16x32_bf16 v[64:67], v[184:187], v[230:233], v[64:67]
	v_mfma_f32_16x16x32_bf16 v[116:119], v[172:175], v[196:199], v[116:119]
	v_mfma_f32_16x16x32_bf16 v[112:115], v[188:191], v[196:199], v[112:115]
	v_mfma_f32_16x16x32_bf16 v[100:103], v[172:175], v[218:221], v[100:103]
	v_mfma_f32_16x16x32_bf16 v[96:99], v[188:191], v[218:221], v[96:99]
	v_mfma_f32_16x16x32_bf16 v[84:87], v[172:175], v[226:229], v[84:87]
	v_mfma_f32_16x16x32_bf16 v[80:83], v[188:191], v[226:229], v[80:83]
	v_mfma_f32_16x16x32_bf16 v[68:71], v[172:175], v[234:237], v[68:71]
	v_mfma_f32_16x16x32_bf16 v[64:67], v[188:191], v[234:237], v[64:67]
	s_setprio 0
	s_barrier
	s_add_i32 s58, s59, s23
	v_lshl_add_u64 v[156:157], s[50:51], 0, v[146:147]
	s_mov_b32 m0, s58
	global_load_lds_dwordx4 v[156:157], off
	s_add_i32 m0, s58, 0x2000
	s_add_u32 s58, s50, 0x40000
	v_lshl_add_u64 v[200:201], s[50:51], 0, v[150:151]
	s_addc_u32 s59, s51, 0
	s_add_i32 s57, s57, s23
	global_load_lds_dwordx4 v[200:201], off
	v_lshl_add_u64 v[238:239], s[58:59], 0, v[146:147]
	s_mov_b32 m0, s57
	v_lshl_add_u64 v[240:241], s[52:53], 0, v[148:149]
	global_load_lds_dwordx4 v[238:239], off
	v_lshl_add_u64 v[238:239], s[58:59], 0, v[150:151]
	s_add_i32 m0, s57, 0x2000
	s_nop 0
	global_load_lds_dwordx4 v[238:239], off
	v_lshl_add_u64 v[238:239], s[52:53], 0, v[144:145]
	s_mov_b32 m0, s33
	s_nop 0
	global_load_lds_dwordx4 v[238:239], off
	s_mov_b32 m0, s83
	s_nop 0
	global_load_lds_dwordx4 v[240:241], off
	ds_read_b128 v[192:195], v163 offset:16384
	ds_read_b128 v[196:199], v163 offset:17408
	ds_read_b128 v[214:217], v163 offset:18432
	ds_read_b128 v[218:221], v163 offset:19456
	ds_read_b128 v[222:225], v163 offset:20480
	ds_read_b128 v[226:229], v163 offset:21504
	ds_read_b128 v[230:233], v163 offset:22528
	ds_read_b128 v[234:237], v163 offset:23552
	s_waitcnt vmcnt(8)
	s_waitcnt lgkmcnt(0)
	s_barrier
	s_setprio 1
	s_waitcnt lgkmcnt(0)
	v_mfma_f32_16x16x32_bf16 v[60:63], v[132:135], v[192:195], v[60:63]
	v_mfma_f32_16x16x32_bf16 v[56:59], v[140:143], v[192:195], v[56:59]
	v_mfma_f32_16x16x32_bf16 v[44:47], v[132:135], v[214:217], v[44:47]
	v_mfma_f32_16x16x32_bf16 v[40:43], v[140:143], v[214:217], v[40:43]
	v_mfma_f32_16x16x32_bf16 v[28:31], v[132:135], v[222:225], v[28:31]
	v_mfma_f32_16x16x32_bf16 v[24:27], v[140:143], v[222:225], v[24:27]
	v_mfma_f32_16x16x32_bf16 v[12:15], v[132:135], v[230:233], v[12:15]
	v_mfma_f32_16x16x32_bf16 v[8:11], v[140:143], v[230:233], v[8:11]
	v_mfma_f32_16x16x32_bf16 v[60:63], v[136:139], v[196:199], v[60:63]
	v_mfma_f32_16x16x32_bf16 v[56:59], v[164:167], v[196:199], v[56:59]
	v_mfma_f32_16x16x32_bf16 v[44:47], v[136:139], v[218:221], v[44:47]
	v_mfma_f32_16x16x32_bf16 v[40:43], v[164:167], v[218:221], v[40:43]
	v_mfma_f32_16x16x32_bf16 v[28:31], v[136:139], v[226:229], v[28:31]
	v_mfma_f32_16x16x32_bf16 v[24:27], v[164:167], v[226:229], v[24:27]
	v_mfma_f32_16x16x32_bf16 v[12:15], v[136:139], v[234:237], v[12:15]
	v_mfma_f32_16x16x32_bf16 v[8:11], v[164:167], v[234:237], v[8:11]
	s_setprio 0
	s_setprio 1
	v_mfma_f32_16x16x32_bf16 v[52:55], v[168:171], v[192:195], v[52:55]
	v_mfma_f32_16x16x32_bf16 v[48:51], v[184:187], v[192:195], v[48:51]
	v_mfma_f32_16x16x32_bf16 v[36:39], v[168:171], v[214:217], v[36:39]
	v_mfma_f32_16x16x32_bf16 v[32:35], v[184:187], v[214:217], v[32:35]
	v_mfma_f32_16x16x32_bf16 v[20:23], v[168:171], v[222:225], v[20:23]
	v_mfma_f32_16x16x32_bf16 v[16:19], v[184:187], v[222:225], v[16:19]
	v_mfma_f32_16x16x32_bf16 v[4:7], v[168:171], v[230:233], v[4:7]
	v_mfma_f32_16x16x32_bf16 v[0:3], v[184:187], v[230:233], v[0:3]
	v_mfma_f32_16x16x32_bf16 v[52:55], v[172:175], v[196:199], v[52:55]
	v_mfma_f32_16x16x32_bf16 v[48:51], v[188:191], v[196:199], v[48:51]
	v_mfma_f32_16x16x32_bf16 v[36:39], v[172:175], v[218:221], v[36:39]
	v_mfma_f32_16x16x32_bf16 v[32:35], v[188:191], v[218:221], v[32:35]
	v_mfma_f32_16x16x32_bf16 v[20:23], v[172:175], v[226:229], v[20:23]
	v_mfma_f32_16x16x32_bf16 v[16:19], v[188:191], v[226:229], v[16:19]
	v_mfma_f32_16x16x32_bf16 v[4:7], v[172:175], v[234:237], v[4:7]
	v_mfma_f32_16x16x32_bf16 v[0:3], v[188:191], v[234:237], v[0:3]
	s_setprio 0
	s_barrier
	s_add_i32 s57, 0, 0x18000
	v_add_u32_e32 v158, s57, v161
	s_add_i32 s58, 0, 0x1c000
	ds_read_b128 v[132:135], v158
	ds_read_b128 v[136:139], v158 offset:1024
	ds_read_b128 v[140:143], v158 offset:2048
	ds_read_b128 v[164:167], v158 offset:3072
	v_add_u32_e32 v158, s58, v161
	ds_read_b128 v[168:171], v158
	ds_read_b128 v[172:175], v158 offset:1024
	ds_read_b128 v[184:187], v158 offset:2048
	ds_read_b128 v[188:191], v158 offset:3072
	s_add_u32 s52, s52, s0
	s_addc_u32 s53, s53, s1
	s_mov_b32 m0, s84
	v_lshl_add_u64 v[242:243], s[52:53], 0, v[144:145]
	ds_read_b128 v[192:195], v163 offset:32768
	ds_read_b128 v[196:199], v163 offset:33792
	ds_read_b128 v[214:217], v163 offset:34816
	ds_read_b128 v[218:221], v163 offset:35840
	ds_read_b128 v[222:225], v163 offset:36864
	ds_read_b128 v[226:229], v163 offset:37888
	ds_read_b128 v[230:233], v163 offset:38912
	ds_read_b128 v[234:237], v163 offset:39936
	global_load_lds_dwordx4 v[242:243], off
	v_lshl_add_u64 v[242:243], s[52:53], 0, v[148:149]
	s_mov_b32 m0, s85
	s_nop 0
	global_load_lds_dwordx4 v[242:243], off
	s_waitcnt vmcnt(8)
	s_waitcnt lgkmcnt(0)
	s_barrier
	s_setprio 1
	s_waitcnt lgkmcnt(0)
	v_mfma_f32_16x16x32_bf16 v[124:127], v[132:135], v[192:195], v[124:127]
	v_mfma_f32_16x16x32_bf16 v[120:123], v[140:143], v[192:195], v[120:123]
	v_mfma_f32_16x16x32_bf16 v[108:111], v[132:135], v[214:217], v[108:111]
	v_mfma_f32_16x16x32_bf16 v[104:107], v[140:143], v[214:217], v[104:107]
	v_mfma_f32_16x16x32_bf16 v[92:95], v[132:135], v[222:225], v[92:95]
	v_mfma_f32_16x16x32_bf16 v[88:91], v[140:143], v[222:225], v[88:91]
	v_mfma_f32_16x16x32_bf16 v[76:79], v[132:135], v[230:233], v[76:79]
	v_mfma_f32_16x16x32_bf16 v[72:75], v[140:143], v[230:233], v[72:75]
	v_mfma_f32_16x16x32_bf16 v[124:127], v[136:139], v[196:199], v[124:127]
	v_mfma_f32_16x16x32_bf16 v[120:123], v[164:167], v[196:199], v[120:123]
	v_mfma_f32_16x16x32_bf16 v[108:111], v[136:139], v[218:221], v[108:111]
	v_mfma_f32_16x16x32_bf16 v[104:107], v[164:167], v[218:221], v[104:107]
	v_mfma_f32_16x16x32_bf16 v[92:95], v[136:139], v[226:229], v[92:95]
	v_mfma_f32_16x16x32_bf16 v[88:91], v[164:167], v[226:229], v[88:91]
	v_mfma_f32_16x16x32_bf16 v[76:79], v[136:139], v[234:237], v[76:79]
	v_mfma_f32_16x16x32_bf16 v[72:75], v[164:167], v[234:237], v[72:75]
	s_setprio 0
	s_setprio 1
	v_mfma_f32_16x16x32_bf16 v[116:119], v[168:171], v[192:195], v[116:119]
	v_mfma_f32_16x16x32_bf16 v[112:115], v[184:187], v[192:195], v[112:115]
	v_mfma_f32_16x16x32_bf16 v[100:103], v[168:171], v[214:217], v[100:103]
	v_mfma_f32_16x16x32_bf16 v[96:99], v[184:187], v[214:217], v[96:99]
	v_mfma_f32_16x16x32_bf16 v[84:87], v[168:171], v[222:225], v[84:87]
	v_mfma_f32_16x16x32_bf16 v[80:83], v[184:187], v[222:225], v[80:83]
	v_mfma_f32_16x16x32_bf16 v[68:71], v[168:171], v[230:233], v[68:71]
	v_mfma_f32_16x16x32_bf16 v[64:67], v[184:187], v[230:233], v[64:67]
	v_mfma_f32_16x16x32_bf16 v[116:119], v[172:175], v[196:199], v[116:119]
	v_mfma_f32_16x16x32_bf16 v[112:115], v[188:191], v[196:199], v[112:115]
	v_mfma_f32_16x16x32_bf16 v[100:103], v[172:175], v[218:221], v[100:103]
	v_mfma_f32_16x16x32_bf16 v[96:99], v[188:191], v[218:221], v[96:99]
	v_mfma_f32_16x16x32_bf16 v[84:87], v[172:175], v[226:229], v[84:87]
	v_mfma_f32_16x16x32_bf16 v[80:83], v[188:191], v[226:229], v[80:83]
	v_mfma_f32_16x16x32_bf16 v[68:71], v[172:175], v[234:237], v[68:71]
	v_mfma_f32_16x16x32_bf16 v[64:67], v[188:191], v[234:237], v[64:67]
	s_setprio 0
	s_barrier
	s_add_i32 s52, s57, s23
	v_lshl_add_u64 v[156:157], v[156:157], 0, s[64:65]
	s_mov_b32 m0, s52
	global_load_lds_dwordx4 v[156:157], off
	s_add_i32 m0, s52, 0x2000
	s_add_u32 s50, s50, 0x40080
	v_lshl_add_u64 v[156:157], v[200:201], 0, s[64:65]
	s_addc_u32 s51, s51, 0
	s_add_i32 s52, s58, s23
	global_load_lds_dwordx4 v[156:157], off
	v_lshl_add_u64 v[156:157], s[50:51], 0, v[146:147]
	s_mov_b32 m0, s52
	s_nop 0
	global_load_lds_dwordx4 v[156:157], off
	v_lshl_add_u64 v[156:157], s[50:51], 0, v[150:151]
	s_add_i32 m0, s52, 0x2000
	s_nop 0
	global_load_lds_dwordx4 v[156:157], off
	v_lshl_add_u64 v[156:157], v[238:239], 0, s[64:65]
	s_mov_b32 m0, s88
	s_nop 0
	global_load_lds_dwordx4 v[156:157], off
	v_lshl_add_u64 v[156:157], v[240:241], 0, s[64:65]
	s_mov_b32 m0, s89
	s_nop 0
	global_load_lds_dwordx4 v[156:157], off
	ds_read_b128 v[192:195], v163 offset:49152
	ds_read_b128 v[196:199], v163 offset:50176
	ds_read_b128 v[214:217], v163 offset:51200
	ds_read_b128 v[218:221], v163 offset:52224
	ds_read_b128 v[222:225], v163 offset:53248
	ds_read_b128 v[226:229], v163 offset:54272
	ds_read_b128 v[230:233], v163 offset:55296
	ds_read_b128 v[234:237], v163 offset:56320
	s_waitcnt vmcnt(8)
	s_waitcnt lgkmcnt(0)
	s_barrier
	s_setprio 1
	s_waitcnt lgkmcnt(0)
	v_mfma_f32_16x16x32_bf16 v[60:63], v[132:135], v[192:195], v[60:63]
	v_mfma_f32_16x16x32_bf16 v[56:59], v[140:143], v[192:195], v[56:59]
	v_mfma_f32_16x16x32_bf16 v[44:47], v[132:135], v[214:217], v[44:47]
	v_mfma_f32_16x16x32_bf16 v[40:43], v[140:143], v[214:217], v[40:43]
	v_mfma_f32_16x16x32_bf16 v[28:31], v[132:135], v[222:225], v[28:31]
	v_mfma_f32_16x16x32_bf16 v[24:27], v[140:143], v[222:225], v[24:27]
	v_mfma_f32_16x16x32_bf16 v[12:15], v[132:135], v[230:233], v[12:15]
	v_mfma_f32_16x16x32_bf16 v[8:11], v[140:143], v[230:233], v[8:11]
	v_mfma_f32_16x16x32_bf16 v[60:63], v[136:139], v[196:199], v[60:63]
	v_mfma_f32_16x16x32_bf16 v[56:59], v[164:167], v[196:199], v[56:59]
	v_mfma_f32_16x16x32_bf16 v[44:47], v[136:139], v[218:221], v[44:47]
	v_mfma_f32_16x16x32_bf16 v[40:43], v[164:167], v[218:221], v[40:43]
	v_mfma_f32_16x16x32_bf16 v[28:31], v[136:139], v[226:229], v[28:31]
	v_mfma_f32_16x16x32_bf16 v[24:27], v[164:167], v[226:229], v[24:27]
	v_mfma_f32_16x16x32_bf16 v[12:15], v[136:139], v[234:237], v[12:15]
	v_mfma_f32_16x16x32_bf16 v[8:11], v[164:167], v[234:237], v[8:11]
	s_setprio 0
	s_setprio 1
	v_mfma_f32_16x16x32_bf16 v[52:55], v[168:171], v[192:195], v[52:55]
	v_mfma_f32_16x16x32_bf16 v[48:51], v[184:187], v[192:195], v[48:51]
	v_mfma_f32_16x16x32_bf16 v[36:39], v[168:171], v[214:217], v[36:39]
	v_mfma_f32_16x16x32_bf16 v[32:35], v[184:187], v[214:217], v[32:35]
	v_mfma_f32_16x16x32_bf16 v[20:23], v[168:171], v[222:225], v[20:23]
	v_mfma_f32_16x16x32_bf16 v[16:19], v[184:187], v[222:225], v[16:19]
	v_mfma_f32_16x16x32_bf16 v[4:7], v[168:171], v[230:233], v[4:7]
	v_mfma_f32_16x16x32_bf16 v[0:3], v[184:187], v[230:233], v[0:3]
	v_mfma_f32_16x16x32_bf16 v[52:55], v[172:175], v[196:199], v[52:55]
	v_mfma_f32_16x16x32_bf16 v[48:51], v[188:191], v[196:199], v[48:51]
	v_mfma_f32_16x16x32_bf16 v[36:39], v[172:175], v[218:221], v[36:39]
	v_mfma_f32_16x16x32_bf16 v[32:35], v[188:191], v[218:221], v[32:35]
	v_mfma_f32_16x16x32_bf16 v[20:23], v[172:175], v[226:229], v[20:23]
	v_mfma_f32_16x16x32_bf16 v[16:19], v[188:191], v[226:229], v[16:19]
	v_mfma_f32_16x16x32_bf16 v[4:7], v[172:175], v[234:237], v[4:7]
	v_mfma_f32_16x16x32_bf16 v[0:3], v[188:191], v[234:237], v[0:3]
	s_setprio 0
	s_barrier
	s_add_i32 vcc_lo, vcc_lo, 2
	s_add_u32 s48, s48, 0x100
	s_addc_u32 s49, s49, 0
	s_cmp_gt_u32 vcc_lo, 13
	s_cbranch_scc0 .LBB0_582
	s_and_b64 vcc, exec, s[36:37]
	s_cbranch_vccz .LBB0_585
	s_barrier

.LBB0_635:
	s_add_u32 s4, s2, 0xfffc0080
	s_addc_u32 s5, s3, -1
	s_add_i32 s33, 0, 0x10000
	s_cmp_eq_u32 s9, 12
	s_cselect_b32 s7, s49, s5
	s_cselect_b32 s6, s48, s4
	s_cselect_b32 s5, s51, s8
	s_cselect_b32 s4, s50, s1
	s_add_i32 s54, 0, 0x14000
	v_add_u32_e32 v76, s33, v194
	v_add_u32_e32 v156, s54, v194
	v_lshl_add_u64 v[192:193], s[2:3], 0, v[168:169]
	s_add_i32 m0, s21, 0xc000
	global_load_lds_dwordx4 v[192:193], off
	v_lshl_add_u64 v[192:193], s[2:3], 0, v[170:171]
	s_add_i32 m0, s21, 0xe000
	s_nop 0
	global_load_lds_dwordx4 v[192:193], off
	ds_read_b128 v[32:35], v76
	ds_read_b128 v[36:39], v76 offset:1024
	ds_read_b128 v[72:75], v76 offset:2048
	ds_read_b128 v[76:79], v76 offset:3072
	ds_read_b128 v[112:115], v156
	ds_read_b128 v[116:119], v156 offset:1024
	ds_read_b128 v[152:155], v156 offset:2048
	ds_read_b128 v[156:159], v156 offset:3072
	ds_read_b128 v[172:175], v195
	ds_read_b128 v[184:187], v195 offset:1024
	ds_read_b128 v[188:191], v195 offset:2048
	ds_read_b128 v[196:199], v195 offset:3072
	ds_read_b128 v[214:217], v195 offset:4096
	ds_read_b128 v[218:221], v195 offset:5120
	ds_read_b128 v[222:225], v195 offset:6144
	ds_read_b128 v[226:229], v195 offset:7168
	s_waitcnt vmcnt(8)
	s_waitcnt lgkmcnt(0)
	s_barrier
	s_setprio 1
	s_waitcnt lgkmcnt(0)
	v_mfma_f32_16x16x32_bf16 v[148:151], v[32:35], v[172:175], v[148:151]
	v_mfma_f32_16x16x32_bf16 v[144:147], v[72:75], v[172:175], v[144:147]
	v_mfma_f32_16x16x32_bf16 v[132:135], v[32:35], v[188:191], v[132:135]
	v_mfma_f32_16x16x32_bf16 v[128:131], v[72:75], v[188:191], v[128:131]
	v_mfma_f32_16x16x32_bf16 v[108:111], v[32:35], v[214:217], v[108:111]
	v_mfma_f32_16x16x32_bf16 v[104:107], v[72:75], v[214:217], v[104:107]
	v_mfma_f32_16x16x32_bf16 v[92:95], v[32:35], v[222:225], v[92:95]
	v_mfma_f32_16x16x32_bf16 v[88:91], v[72:75], v[222:225], v[88:91]
	v_mfma_f32_16x16x32_bf16 v[148:151], v[36:39], v[184:187], v[148:151]
	v_mfma_f32_16x16x32_bf16 v[144:147], v[76:79], v[184:187], v[144:147]
	v_mfma_f32_16x16x32_bf16 v[132:135], v[36:39], v[196:199], v[132:135]
	v_mfma_f32_16x16x32_bf16 v[128:131], v[76:79], v[196:199], v[128:131]
	v_mfma_f32_16x16x32_bf16 v[108:111], v[36:39], v[218:221], v[108:111]
	v_mfma_f32_16x16x32_bf16 v[104:107], v[76:79], v[218:221], v[104:107]
	v_mfma_f32_16x16x32_bf16 v[92:95], v[36:39], v[226:229], v[92:95]
	v_mfma_f32_16x16x32_bf16 v[88:91], v[76:79], v[226:229], v[88:91]
	s_setprio 0
	s_setprio 1
	v_mfma_f32_16x16x32_bf16 v[140:143], v[112:115], v[172:175], v[140:143]
	v_mfma_f32_16x16x32_bf16 v[136:139], v[152:155], v[172:175], v[136:139]
	v_mfma_f32_16x16x32_bf16 v[124:127], v[112:115], v[188:191], v[124:127]
	v_mfma_f32_16x16x32_bf16 v[120:123], v[152:155], v[188:191], v[120:123]
	v_mfma_f32_16x16x32_bf16 v[100:103], v[112:115], v[214:217], v[100:103]
	v_mfma_f32_16x16x32_bf16 v[96:99], v[152:155], v[214:217], v[96:99]
	v_mfma_f32_16x16x32_bf16 v[84:87], v[112:115], v[222:225], v[84:87]
	v_mfma_f32_16x16x32_bf16 v[80:83], v[152:155], v[222:225], v[80:83]
	v_mfma_f32_16x16x32_bf16 v[140:143], v[116:119], v[184:187], v[140:143]
	v_mfma_f32_16x16x32_bf16 v[136:139], v[156:159], v[184:187], v[136:139]
	v_mfma_f32_16x16x32_bf16 v[124:127], v[116:119], v[196:199], v[124:127]
	v_mfma_f32_16x16x32_bf16 v[120:123], v[156:159], v[196:199], v[120:123]
	v_mfma_f32_16x16x32_bf16 v[100:103], v[116:119], v[218:221], v[100:103]
	v_mfma_f32_16x16x32_bf16 v[96:99], v[156:159], v[218:221], v[96:99]
	v_mfma_f32_16x16x32_bf16 v[84:87], v[116:119], v[226:229], v[84:87]
	v_mfma_f32_16x16x32_bf16 v[80:83], v[156:159], v[226:229], v[80:83]
	s_setprio 0
	s_barrier
	s_add_i32 s33, s33, s13
	v_lshl_add_u64 v[192:193], s[4:5], 0, v[162:163]
	s_mov_b32 m0, s33
	global_load_lds_dwordx4 v[192:193], off
	s_add_i32 m0, s33, 0x2000
	s_add_u32 s36, s4, 0x40000
	v_lshl_add_u64 v[200:201], s[4:5], 0, v[166:167]
	s_addc_u32 s37, s5, 0
	s_add_i32 s33, s54, s13
	global_load_lds_dwordx4 v[200:201], off
	v_lshl_add_u64 v[230:231], s[36:37], 0, v[162:163]
	s_mov_b32 m0, s33
	v_lshl_add_u64 v[232:233], s[6:7], 0, v[164:165]
	global_load_lds_dwordx4 v[230:231], off
	v_lshl_add_u64 v[230:231], s[36:37], 0, v[166:167]
	s_add_i32 m0, s33, 0x2000
	s_nop 0
	global_load_lds_dwordx4 v[230:231], off
	v_lshl_add_u64 v[230:231], s[6:7], 0, v[160:161]
	s_mov_b32 m0, s21
	s_nop 0
	global_load_lds_dwordx4 v[230:231], off
	s_mov_b32 m0, s23
	s_nop 0
	global_load_lds_dwordx4 v[232:233], off
	ds_read_b128 v[172:175], v195 offset:16384
	ds_read_b128 v[184:187], v195 offset:17408
	ds_read_b128 v[188:191], v195 offset:18432
	ds_read_b128 v[196:199], v195 offset:19456
	ds_read_b128 v[214:217], v195 offset:20480
	ds_read_b128 v[218:221], v195 offset:21504
	ds_read_b128 v[222:225], v195 offset:22528
	ds_read_b128 v[226:229], v195 offset:23552
	s_waitcnt vmcnt(8)
	s_waitcnt lgkmcnt(0)
	s_barrier
	s_setprio 1
	s_waitcnt lgkmcnt(0)
	v_mfma_f32_16x16x32_bf16 v[68:71], v[32:35], v[172:175], v[68:71]
	v_mfma_f32_16x16x32_bf16 v[64:67], v[72:75], v[172:175], v[64:67]
	v_mfma_f32_16x16x32_bf16 v[52:55], v[32:35], v[188:191], v[52:55]
	v_mfma_f32_16x16x32_bf16 v[48:51], v[72:75], v[188:191], v[48:51]
	v_mfma_f32_16x16x32_bf16 v[28:31], v[32:35], v[214:217], v[28:31]
	v_mfma_f32_16x16x32_bf16 v[24:27], v[72:75], v[214:217], v[24:27]
	v_mfma_f32_16x16x32_bf16 v[12:15], v[32:35], v[222:225], v[12:15]
	v_mfma_f32_16x16x32_bf16 v[8:11], v[72:75], v[222:225], v[8:11]
	v_mfma_f32_16x16x32_bf16 v[68:71], v[36:39], v[184:187], v[68:71]
	v_mfma_f32_16x16x32_bf16 v[64:67], v[76:79], v[184:187], v[64:67]
	v_mfma_f32_16x16x32_bf16 v[52:55], v[36:39], v[196:199], v[52:55]
	v_mfma_f32_16x16x32_bf16 v[48:51], v[76:79], v[196:199], v[48:51]
	v_mfma_f32_16x16x32_bf16 v[28:31], v[36:39], v[218:221], v[28:31]
	v_mfma_f32_16x16x32_bf16 v[24:27], v[76:79], v[218:221], v[24:27]
	v_mfma_f32_16x16x32_bf16 v[12:15], v[36:39], v[226:229], v[12:15]
	v_mfma_f32_16x16x32_bf16 v[8:11], v[76:79], v[226:229], v[8:11]
	s_setprio 0
	s_setprio 1
	v_mfma_f32_16x16x32_bf16 v[44:47], v[112:115], v[188:191], v[44:47]
	v_mfma_f32_16x16x32_bf16 v[40:43], v[152:155], v[188:191], v[40:43]
	v_mfma_f32_16x16x32_bf16 v[20:23], v[112:115], v[214:217], v[20:23]
	v_mfma_f32_16x16x32_bf16 v[16:19], v[152:155], v[214:217], v[16:19]
	v_mfma_f32_16x16x32_bf16 v[4:7], v[112:115], v[222:225], v[4:7]
	v_mfma_f32_16x16x32_bf16 v[0:3], v[152:155], v[222:225], v[0:3]
	v_mfma_f32_16x16x32_bf16 v[32:35], v[112:115], v[172:175], v[60:63]
	v_mfma_f32_16x16x32_bf16 v[36:39], v[152:155], v[172:175], v[56:59]
	v_mfma_f32_16x16x32_bf16 v[44:47], v[116:119], v[196:199], v[44:47]
	v_mfma_f32_16x16x32_bf16 v[40:43], v[156:159], v[196:199], v[40:43]
	v_mfma_f32_16x16x32_bf16 v[20:23], v[116:119], v[218:221], v[20:23]
	v_mfma_f32_16x16x32_bf16 v[16:19], v[156:159], v[218:221], v[16:19]
	v_mfma_f32_16x16x32_bf16 v[4:7], v[116:119], v[226:229], v[4:7]
	v_mfma_f32_16x16x32_bf16 v[0:3], v[156:159], v[226:229], v[0:3]
	v_mfma_f32_16x16x32_bf16 v[32:35], v[116:119], v[184:187], v[32:35]
	v_mfma_f32_16x16x32_bf16 v[36:39], v[156:159], v[184:187], v[36:39]
	s_setprio 0
	s_barrier
	s_add_i32 s33, 0, 0x18000
	s_add_i32 s36, 0, 0x1c000
	v_add_u32_e32 v76, s33, v194
	v_add_u32_e32 v156, s36, v194
	s_add_u32 s6, s6, 0x40000
	s_addc_u32 s7, s7, 0
	s_mov_b32 m0, s52
	v_lshl_add_u64 v[234:235], s[6:7], 0, v[160:161]
	global_load_lds_dwordx4 v[234:235], off
	v_lshl_add_u64 v[234:235], s[6:7], 0, v[164:165]
	s_mov_b32 m0, s53
	s_nop 0
	global_load_lds_dwordx4 v[234:235], off
	ds_read_b128 v[56:59], v76
	ds_read_b128 v[60:63], v76 offset:1024
	ds_read_b128 v[72:75], v76 offset:2048
	ds_read_b128 v[76:79], v76 offset:3072
	ds_read_b128 v[112:115], v156
	ds_read_b128 v[116:119], v156 offset:1024
	ds_read_b128 v[152:155], v156 offset:2048
	ds_read_b128 v[156:159], v156 offset:3072
	ds_read_b128 v[172:175], v195 offset:32768
	ds_read_b128 v[184:187], v195 offset:33792
	ds_read_b128 v[188:191], v195 offset:34816
	ds_read_b128 v[196:199], v195 offset:35840
	ds_read_b128 v[214:217], v195 offset:36864
	ds_read_b128 v[218:221], v195 offset:37888
	ds_read_b128 v[222:225], v195 offset:38912
	ds_read_b128 v[226:229], v195 offset:39936
	s_waitcnt vmcnt(8)
	s_waitcnt lgkmcnt(0)
	s_barrier
	s_setprio 1
	s_waitcnt lgkmcnt(0)
	v_mfma_f32_16x16x32_bf16 v[148:151], v[56:59], v[172:175], v[148:151]
	v_mfma_f32_16x16x32_bf16 v[144:147], v[72:75], v[172:175], v[144:147]
	v_mfma_f32_16x16x32_bf16 v[132:135], v[56:59], v[188:191], v[132:135]
	v_mfma_f32_16x16x32_bf16 v[128:131], v[72:75], v[188:191], v[128:131]
	v_mfma_f32_16x16x32_bf16 v[108:111], v[56:59], v[214:217], v[108:111]
	v_mfma_f32_16x16x32_bf16 v[104:107], v[72:75], v[214:217], v[104:107]
	v_mfma_f32_16x16x32_bf16 v[92:95], v[56:59], v[222:225], v[92:95]
	v_mfma_f32_16x16x32_bf16 v[88:91], v[72:75], v[222:225], v[88:91]
	v_mfma_f32_16x16x32_bf16 v[148:151], v[60:63], v[184:187], v[148:151]
	v_mfma_f32_16x16x32_bf16 v[144:147], v[76:79], v[184:187], v[144:147]
	v_mfma_f32_16x16x32_bf16 v[132:135], v[60:63], v[196:199], v[132:135]
	v_mfma_f32_16x16x32_bf16 v[128:131], v[76:79], v[196:199], v[128:131]
	v_mfma_f32_16x16x32_bf16 v[108:111], v[60:63], v[218:221], v[108:111]
	v_mfma_f32_16x16x32_bf16 v[104:107], v[76:79], v[218:221], v[104:107]
	v_mfma_f32_16x16x32_bf16 v[92:95], v[60:63], v[226:229], v[92:95]
	v_mfma_f32_16x16x32_bf16 v[88:91], v[76:79], v[226:229], v[88:91]
	s_setprio 0
	s_setprio 1
	v_mfma_f32_16x16x32_bf16 v[140:143], v[112:115], v[172:175], v[140:143]
	v_mfma_f32_16x16x32_bf16 v[136:139], v[152:155], v[172:175], v[136:139]
	v_mfma_f32_16x16x32_bf16 v[124:127], v[112:115], v[188:191], v[124:127]
	v_mfma_f32_16x16x32_bf16 v[120:123], v[152:155], v[188:191], v[120:123]
	v_mfma_f32_16x16x32_bf16 v[100:103], v[112:115], v[214:217], v[100:103]
	v_mfma_f32_16x16x32_bf16 v[96:99], v[152:155], v[214:217], v[96:99]
	v_mfma_f32_16x16x32_bf16 v[84:87], v[112:115], v[222:225], v[84:87]
	v_mfma_f32_16x16x32_bf16 v[80:83], v[152:155], v[222:225], v[80:83]
	v_mfma_f32_16x16x32_bf16 v[140:143], v[116:119], v[184:187], v[140:143]
	v_mfma_f32_16x16x32_bf16 v[136:139], v[156:159], v[184:187], v[136:139]
	v_mfma_f32_16x16x32_bf16 v[124:127], v[116:119], v[196:199], v[124:127]
	v_mfma_f32_16x16x32_bf16 v[120:123], v[156:159], v[196:199], v[120:123]
	v_mfma_f32_16x16x32_bf16 v[100:103], v[116:119], v[218:221], v[100:103]
	v_mfma_f32_16x16x32_bf16 v[96:99], v[156:159], v[218:221], v[96:99]
	v_mfma_f32_16x16x32_bf16 v[84:87], v[116:119], v[226:229], v[84:87]
	v_mfma_f32_16x16x32_bf16 v[80:83], v[156:159], v[226:229], v[80:83]
	s_setprio 0
	s_barrier
	s_add_i32 s6, s33, s13
	v_lshl_add_u64 v[192:193], v[192:193], 0, s[58:59]
	s_mov_b32 m0, s6
	global_load_lds_dwordx4 v[192:193], off
	s_add_i32 m0, s6, 0x2000
	s_add_u32 s4, s4, 0x40080
	v_lshl_add_u64 v[192:193], v[200:201], 0, s[58:59]
	s_addc_u32 s5, s5, 0
	s_add_i32 s6, s36, s13
	global_load_lds_dwordx4 v[192:193], off
	v_lshl_add_u64 v[192:193], s[4:5], 0, v[162:163]
	s_mov_b32 m0, s6
	s_nop 0
	global_load_lds_dwordx4 v[192:193], off
	v_lshl_add_u64 v[192:193], s[4:5], 0, v[166:167]
	s_add_i32 m0, s6, 0x2000
	s_nop 0
	global_load_lds_dwordx4 v[192:193], off
	v_lshl_add_u64 v[192:193], v[230:231], 0, s[58:59]
	s_mov_b32 m0, s78
	s_nop 0
	global_load_lds_dwordx4 v[192:193], off
	v_lshl_add_u64 v[192:193], v[232:233], 0, s[58:59]
	s_mov_b32 m0, s79
	s_nop 0
	global_load_lds_dwordx4 v[192:193], off
	ds_read_b128 v[172:175], v195 offset:49152
	ds_read_b128 v[184:187], v195 offset:50176
	ds_read_b128 v[188:191], v195 offset:51200
	ds_read_b128 v[196:199], v195 offset:52224
	ds_read_b128 v[214:217], v195 offset:53248
	ds_read_b128 v[218:221], v195 offset:54272
	ds_read_b128 v[222:225], v195 offset:55296
	ds_read_b128 v[226:229], v195 offset:56320
	s_waitcnt vmcnt(8)
	s_waitcnt lgkmcnt(0)
	s_barrier
	s_setprio 1
	s_waitcnt lgkmcnt(0)
	v_mfma_f32_16x16x32_bf16 v[68:71], v[56:59], v[172:175], v[68:71]
	v_mfma_f32_16x16x32_bf16 v[64:67], v[72:75], v[172:175], v[64:67]
	v_mfma_f32_16x16x32_bf16 v[52:55], v[56:59], v[188:191], v[52:55]
	v_mfma_f32_16x16x32_bf16 v[48:51], v[72:75], v[188:191], v[48:51]
	v_mfma_f32_16x16x32_bf16 v[28:31], v[56:59], v[214:217], v[28:31]
	v_mfma_f32_16x16x32_bf16 v[24:27], v[72:75], v[214:217], v[24:27]
	v_mfma_f32_16x16x32_bf16 v[12:15], v[56:59], v[222:225], v[12:15]
	v_mfma_f32_16x16x32_bf16 v[8:11], v[72:75], v[222:225], v[8:11]
	v_mfma_f32_16x16x32_bf16 v[68:71], v[60:63], v[184:187], v[68:71]
	v_mfma_f32_16x16x32_bf16 v[64:67], v[76:79], v[184:187], v[64:67]
	v_mfma_f32_16x16x32_bf16 v[52:55], v[60:63], v[196:199], v[52:55]
	v_mfma_f32_16x16x32_bf16 v[48:51], v[76:79], v[196:199], v[48:51]
	v_mfma_f32_16x16x32_bf16 v[28:31], v[60:63], v[218:221], v[28:31]
	v_mfma_f32_16x16x32_bf16 v[24:27], v[76:79], v[218:221], v[24:27]
	v_mfma_f32_16x16x32_bf16 v[12:15], v[60:63], v[226:229], v[12:15]
	v_mfma_f32_16x16x32_bf16 v[8:11], v[76:79], v[226:229], v[8:11]
	s_setprio 0
	s_setprio 1
	v_mfma_f32_16x16x32_bf16 v[32:35], v[112:115], v[172:175], v[32:35]
	v_mfma_f32_16x16x32_bf16 v[60:63], v[116:119], v[184:187], v[32:35]
	v_mfma_f32_16x16x32_bf16 v[32:35], v[152:155], v[172:175], v[36:39]
	v_mfma_f32_16x16x32_bf16 v[56:59], v[156:159], v[184:187], v[32:35]
	v_mfma_f32_16x16x32_bf16 v[32:35], v[112:115], v[188:191], v[44:47]
	v_mfma_f32_16x16x32_bf16 v[44:47], v[116:119], v[196:199], v[32:35]
	v_mfma_f32_16x16x32_bf16 v[32:35], v[152:155], v[188:191], v[40:43]
	v_mfma_f32_16x16x32_bf16 v[20:23], v[112:115], v[214:217], v[20:23]
	v_mfma_f32_16x16x32_bf16 v[16:19], v[152:155], v[214:217], v[16:19]
	v_mfma_f32_16x16x32_bf16 v[4:7], v[112:115], v[222:225], v[4:7]
	v_mfma_f32_16x16x32_bf16 v[0:3], v[152:155], v[222:225], v[0:3]
	v_mfma_f32_16x16x32_bf16 v[40:43], v[156:159], v[196:199], v[32:35]
	v_mfma_f32_16x16x32_bf16 v[20:23], v[116:119], v[218:221], v[20:23]
	v_mfma_f32_16x16x32_bf16 v[16:19], v[156:159], v[218:221], v[16:19]
	v_mfma_f32_16x16x32_bf16 v[4:7], v[116:119], v[226:229], v[4:7]
	v_mfma_f32_16x16x32_bf16 v[0:3], v[156:159], v[226:229], v[0:3]
	s_setprio 0
	s_barrier
	s_add_i32 s9, s9, 2
	s_add_u32 s2, s2, 0x100
	s_addc_u32 s3, s3, 0
	s_add_u32 s1, s1, 0x100
	s_addc_u32 s8, s8, 0
	s_cmp_gt_u32 s9, 13
	s_cbranch_scc0 .LBB0_635
	s_mov_b64 s[58:59], 0x80
	s_and_b64 vcc, exec, s[34:35]
	s_cbranch_vccz .LBB0_638
	s_barrier

.LBB0_1010:
	s_add_i32 s31, s6, 2
	s_add_u32 s35, s36, 0x80
	s_addc_u32 s7, s37, 0
	s_add_i32 s52, 0, 0x10000
	s_cmp_eq_u32 s33, s6
	s_cselect_b32 s7, s1, s7
	s_cselect_b32 s6, s0, s35
	s_cselect_b32 s51, s3, s9
	s_cselect_b32 s50, s2, s8
	s_add_i32 s35, 0, 0x14000
	v_add_u32_e32 v140, s52, v213
	v_add_u32_e32 v156, s35, v213
	v_lshl_add_u64 v[200:201], s[36:37], 0, v[192:193]
	s_add_i32 m0, s23, 0xc000
	global_load_lds_dwordx4 v[200:201], off
	v_lshl_add_u64 v[200:201], s[36:37], 0, v[194:195]
	s_add_i32 m0, s23, 0xe000
	s_nop 0
	global_load_lds_dwordx4 v[200:201], off
	ds_read_b128 v[128:131], v140
	ds_read_b128 v[132:135], v140 offset:1024
	ds_read_b128 v[136:139], v140 offset:2048
	ds_read_b128 v[140:143], v140 offset:3072
	ds_read_b128 v[144:147], v156
	ds_read_b128 v[148:151], v156 offset:1024
	ds_read_b128 v[152:155], v156 offset:2048
	ds_read_b128 v[156:159], v156 offset:3072
	ds_read_b128 v[160:163], v214
	ds_read_b128 v[164:167], v214 offset:1024
	ds_read_b128 v[168:171], v214 offset:2048
	ds_read_b128 v[172:175], v214 offset:3072
	ds_read_b128 v[196:199], v214 offset:4096
	ds_read_b128 v[216:219], v214 offset:5120
	ds_read_b128 v[220:223], v214 offset:6144
	ds_read_b128 v[224:227], v214 offset:7168
	s_waitcnt vmcnt(8)
	s_waitcnt lgkmcnt(0)
	s_barrier
	s_setprio 1
	s_waitcnt lgkmcnt(0)
	v_mfma_f32_16x16x32_bf16 v[124:127], v[128:131], v[160:163], v[124:127]
	v_mfma_f32_16x16x32_bf16 v[120:123], v[136:139], v[160:163], v[120:123]
	v_mfma_f32_16x16x32_bf16 v[108:111], v[128:131], v[168:171], v[108:111]
	v_mfma_f32_16x16x32_bf16 v[104:107], v[136:139], v[168:171], v[104:107]
	v_mfma_f32_16x16x32_bf16 v[92:95], v[128:131], v[196:199], v[92:95]
	v_mfma_f32_16x16x32_bf16 v[88:91], v[136:139], v[196:199], v[88:91]
	v_mfma_f32_16x16x32_bf16 v[76:79], v[128:131], v[220:223], v[76:79]
	v_mfma_f32_16x16x32_bf16 v[72:75], v[136:139], v[220:223], v[72:75]
	v_mfma_f32_16x16x32_bf16 v[124:127], v[132:135], v[164:167], v[124:127]
	v_mfma_f32_16x16x32_bf16 v[120:123], v[140:143], v[164:167], v[120:123]
	v_mfma_f32_16x16x32_bf16 v[108:111], v[132:135], v[172:175], v[108:111]
	v_mfma_f32_16x16x32_bf16 v[104:107], v[140:143], v[172:175], v[104:107]
	v_mfma_f32_16x16x32_bf16 v[92:95], v[132:135], v[216:219], v[92:95]
	v_mfma_f32_16x16x32_bf16 v[88:91], v[140:143], v[216:219], v[88:91]
	v_mfma_f32_16x16x32_bf16 v[76:79], v[132:135], v[224:227], v[76:79]
	v_mfma_f32_16x16x32_bf16 v[72:75], v[140:143], v[224:227], v[72:75]
	s_setprio 0
	s_setprio 1
	v_mfma_f32_16x16x32_bf16 v[116:119], v[144:147], v[160:163], v[116:119]
	v_mfma_f32_16x16x32_bf16 v[112:115], v[152:155], v[160:163], v[112:115]
	v_mfma_f32_16x16x32_bf16 v[100:103], v[144:147], v[168:171], v[100:103]
	v_mfma_f32_16x16x32_bf16 v[96:99], v[152:155], v[168:171], v[96:99]
	v_mfma_f32_16x16x32_bf16 v[84:87], v[144:147], v[196:199], v[84:87]
	v_mfma_f32_16x16x32_bf16 v[80:83], v[152:155], v[196:199], v[80:83]
	v_mfma_f32_16x16x32_bf16 v[68:71], v[144:147], v[220:223], v[68:71]
	v_mfma_f32_16x16x32_bf16 v[64:67], v[152:155], v[220:223], v[64:67]
	v_mfma_f32_16x16x32_bf16 v[116:119], v[148:151], v[164:167], v[116:119]
	v_mfma_f32_16x16x32_bf16 v[112:115], v[156:159], v[164:167], v[112:115]
	v_mfma_f32_16x16x32_bf16 v[100:103], v[148:151], v[172:175], v[100:103]
	v_mfma_f32_16x16x32_bf16 v[96:99], v[156:159], v[172:175], v[96:99]
	v_mfma_f32_16x16x32_bf16 v[84:87], v[148:151], v[216:219], v[84:87]
	v_mfma_f32_16x16x32_bf16 v[80:83], v[156:159], v[216:219], v[80:83]
	v_mfma_f32_16x16x32_bf16 v[68:71], v[148:151], v[224:227], v[68:71]
	v_mfma_f32_16x16x32_bf16 v[64:67], v[156:159], v[224:227], v[64:67]
	s_setprio 0
	s_barrier
	s_add_i32 s52, s52, s21
	v_lshl_add_u64 v[200:201], s[50:51], 0, v[186:187]
	s_mov_b32 m0, s52
	global_load_lds_dwordx4 v[200:201], off
	s_add_i32 m0, s52, 0x2000
	v_lshl_add_u64 v[228:229], s[50:51], 0, v[190:191]
	s_add_u32 s50, s50, s58
	s_addc_u32 s51, s51, 0
	s_add_i32 s35, s35, s21
	global_load_lds_dwordx4 v[228:229], off
	v_lshl_add_u64 v[230:231], s[50:51], 0, v[186:187]
	s_mov_b32 m0, s35
	v_lshl_add_u64 v[232:233], s[50:51], 0, v[190:191]
	global_load_lds_dwordx4 v[230:231], off
	s_add_i32 m0, s35, 0x2000
	v_lshl_add_u64 v[234:235], s[6:7], 0, v[184:185]
	global_load_lds_dwordx4 v[232:233], off
	s_mov_b32 m0, s23
	v_lshl_add_u64 v[236:237], s[6:7], 0, v[188:189]
	global_load_lds_dwordx4 v[234:235], off
	s_mov_b32 m0, s55
	s_nop 0
	global_load_lds_dwordx4 v[236:237], off
	ds_read_b128 v[160:163], v214 offset:16384
	ds_read_b128 v[164:167], v214 offset:17408
	ds_read_b128 v[168:171], v214 offset:18432
	ds_read_b128 v[172:175], v214 offset:19456
	ds_read_b128 v[196:199], v214 offset:20480
	ds_read_b128 v[216:219], v214 offset:21504
	ds_read_b128 v[220:223], v214 offset:22528
	ds_read_b128 v[224:227], v214 offset:23552
	s_waitcnt vmcnt(8)
	s_waitcnt lgkmcnt(0)
	s_barrier
	s_setprio 1
	s_waitcnt lgkmcnt(0)
	v_mfma_f32_16x16x32_bf16 v[60:63], v[128:131], v[160:163], v[60:63]
	v_mfma_f32_16x16x32_bf16 v[56:59], v[136:139], v[160:163], v[56:59]
	v_mfma_f32_16x16x32_bf16 v[44:47], v[128:131], v[168:171], v[44:47]
	v_mfma_f32_16x16x32_bf16 v[40:43], v[136:139], v[168:171], v[40:43]
	v_mfma_f32_16x16x32_bf16 v[28:31], v[128:131], v[196:199], v[28:31]
	v_mfma_f32_16x16x32_bf16 v[24:27], v[136:139], v[196:199], v[24:27]
	v_mfma_f32_16x16x32_bf16 v[12:15], v[128:131], v[220:223], v[12:15]
	v_mfma_f32_16x16x32_bf16 v[8:11], v[136:139], v[220:223], v[8:11]
	v_mfma_f32_16x16x32_bf16 v[60:63], v[132:135], v[164:167], v[60:63]
	v_mfma_f32_16x16x32_bf16 v[56:59], v[140:143], v[164:167], v[56:59]
	v_mfma_f32_16x16x32_bf16 v[44:47], v[132:135], v[172:175], v[44:47]
	v_mfma_f32_16x16x32_bf16 v[40:43], v[140:143], v[172:175], v[40:43]
	v_mfma_f32_16x16x32_bf16 v[28:31], v[132:135], v[216:219], v[28:31]
	v_mfma_f32_16x16x32_bf16 v[24:27], v[140:143], v[216:219], v[24:27]
	v_mfma_f32_16x16x32_bf16 v[12:15], v[132:135], v[224:227], v[12:15]
	v_mfma_f32_16x16x32_bf16 v[8:11], v[140:143], v[224:227], v[8:11]
	s_setprio 0
	s_setprio 1
	v_mfma_f32_16x16x32_bf16 v[52:55], v[144:147], v[160:163], v[52:55]
	v_mfma_f32_16x16x32_bf16 v[48:51], v[152:155], v[160:163], v[48:51]
	v_mfma_f32_16x16x32_bf16 v[36:39], v[144:147], v[168:171], v[36:39]
	v_mfma_f32_16x16x32_bf16 v[32:35], v[152:155], v[168:171], v[32:35]
	v_mfma_f32_16x16x32_bf16 v[20:23], v[144:147], v[196:199], v[20:23]
	v_mfma_f32_16x16x32_bf16 v[16:19], v[152:155], v[196:199], v[16:19]
	v_mfma_f32_16x16x32_bf16 v[4:7], v[144:147], v[220:223], v[4:7]
	v_mfma_f32_16x16x32_bf16 v[0:3], v[152:155], v[220:223], v[0:3]
	v_mfma_f32_16x16x32_bf16 v[52:55], v[148:151], v[164:167], v[52:55]
	v_mfma_f32_16x16x32_bf16 v[48:51], v[156:159], v[164:167], v[48:51]
	v_mfma_f32_16x16x32_bf16 v[36:39], v[148:151], v[172:175], v[36:39]
	v_mfma_f32_16x16x32_bf16 v[32:35], v[156:159], v[172:175], v[32:35]
	v_mfma_f32_16x16x32_bf16 v[20:23], v[148:151], v[216:219], v[20:23]
	v_mfma_f32_16x16x32_bf16 v[16:19], v[156:159], v[216:219], v[16:19]
	v_mfma_f32_16x16x32_bf16 v[4:7], v[148:151], v[224:227], v[4:7]
	v_mfma_f32_16x16x32_bf16 v[0:3], v[156:159], v[224:227], v[0:3]
	s_setprio 0
	s_barrier
	s_add_i32 s35, 0, 0x18000
	s_add_i32 s50, 0, 0x1c000
	v_add_u32_e32 v140, s35, v213
	v_add_u32_e32 v156, s50, v213
	s_add_u32 s6, s6, s58
	s_addc_u32 s7, s7, 0
	s_mov_b32 m0, s78
	v_lshl_add_u64 v[238:239], s[6:7], 0, v[184:185]
	global_load_lds_dwordx4 v[238:239], off
	v_lshl_add_u64 v[238:239], s[6:7], 0, v[188:189]
	s_mov_b32 m0, s79
	s_nop 0
	global_load_lds_dwordx4 v[238:239], off
	ds_read_b128 v[128:131], v140
	ds_read_b128 v[132:135], v140 offset:1024
	ds_read_b128 v[136:139], v140 offset:2048
	ds_read_b128 v[140:143], v140 offset:3072
	ds_read_b128 v[144:147], v156
	ds_read_b128 v[148:151], v156 offset:1024
	ds_read_b128 v[152:155], v156 offset:2048
	ds_read_b128 v[156:159], v156 offset:3072
	ds_read_b128 v[160:163], v214 offset:32768
	ds_read_b128 v[164:167], v214 offset:33792
	ds_read_b128 v[168:171], v214 offset:34816
	ds_read_b128 v[172:175], v214 offset:35840
	ds_read_b128 v[196:199], v214 offset:36864
	ds_read_b128 v[216:219], v214 offset:37888
	ds_read_b128 v[220:223], v214 offset:38912
	ds_read_b128 v[224:227], v214 offset:39936
	s_waitcnt vmcnt(8)
	s_waitcnt lgkmcnt(0)
	s_barrier
	s_setprio 1
	s_waitcnt lgkmcnt(0)
	v_mfma_f32_16x16x32_bf16 v[124:127], v[128:131], v[160:163], v[124:127]
	v_mfma_f32_16x16x32_bf16 v[120:123], v[136:139], v[160:163], v[120:123]
	v_mfma_f32_16x16x32_bf16 v[108:111], v[128:131], v[168:171], v[108:111]
	v_mfma_f32_16x16x32_bf16 v[104:107], v[136:139], v[168:171], v[104:107]
	v_mfma_f32_16x16x32_bf16 v[92:95], v[128:131], v[196:199], v[92:95]
	v_mfma_f32_16x16x32_bf16 v[88:91], v[136:139], v[196:199], v[88:91]
	v_mfma_f32_16x16x32_bf16 v[76:79], v[128:131], v[220:223], v[76:79]
	v_mfma_f32_16x16x32_bf16 v[72:75], v[136:139], v[220:223], v[72:75]
	v_mfma_f32_16x16x32_bf16 v[124:127], v[132:135], v[164:167], v[124:127]
	v_mfma_f32_16x16x32_bf16 v[120:123], v[140:143], v[164:167], v[120:123]
	v_mfma_f32_16x16x32_bf16 v[108:111], v[132:135], v[172:175], v[108:111]
	v_mfma_f32_16x16x32_bf16 v[104:107], v[140:143], v[172:175], v[104:107]
	v_mfma_f32_16x16x32_bf16 v[92:95], v[132:135], v[216:219], v[92:95]
	v_mfma_f32_16x16x32_bf16 v[88:91], v[140:143], v[216:219], v[88:91]
	v_mfma_f32_16x16x32_bf16 v[76:79], v[132:135], v[224:227], v[76:79]
	v_mfma_f32_16x16x32_bf16 v[72:75], v[140:143], v[224:227], v[72:75]
	s_setprio 0
	s_setprio 1
	v_mfma_f32_16x16x32_bf16 v[116:119], v[144:147], v[160:163], v[116:119]
	v_mfma_f32_16x16x32_bf16 v[112:115], v[152:155], v[160:163], v[112:115]
	v_mfma_f32_16x16x32_bf16 v[100:103], v[144:147], v[168:171], v[100:103]
	v_mfma_f32_16x16x32_bf16 v[96:99], v[152:155], v[168:171], v[96:99]
	v_mfma_f32_16x16x32_bf16 v[84:87], v[144:147], v[196:199], v[84:87]
	v_mfma_f32_16x16x32_bf16 v[80:83], v[152:155], v[196:199], v[80:83]
	v_mfma_f32_16x16x32_bf16 v[68:71], v[144:147], v[220:223], v[68:71]
	v_mfma_f32_16x16x32_bf16 v[64:67], v[152:155], v[220:223], v[64:67]
	v_mfma_f32_16x16x32_bf16 v[116:119], v[148:151], v[164:167], v[116:119]
	v_mfma_f32_16x16x32_bf16 v[112:115], v[156:159], v[164:167], v[112:115]
	v_mfma_f32_16x16x32_bf16 v[100:103], v[148:151], v[172:175], v[100:103]
	v_mfma_f32_16x16x32_bf16 v[96:99], v[156:159], v[172:175], v[96:99]
	v_mfma_f32_16x16x32_bf16 v[84:87], v[148:151], v[216:219], v[84:87]
	v_mfma_f32_16x16x32_bf16 v[80:83], v[156:159], v[216:219], v[80:83]
	v_mfma_f32_16x16x32_bf16 v[68:71], v[148:151], v[224:227], v[68:71]
	v_mfma_f32_16x16x32_bf16 v[64:67], v[156:159], v[224:227], v[64:67]
	s_setprio 0
	s_barrier
	s_add_i32 s6, s35, s21
	v_lshl_add_u64 v[200:201], v[200:201], 0, s[64:65]
	s_mov_b32 m0, s6
	global_load_lds_dwordx4 v[200:201], off
	v_lshl_add_u64 v[200:201], v[228:229], 0, s[64:65]
	s_add_i32 m0, s6, 0x2000
	s_add_i32 s6, s50, s21
	global_load_lds_dwordx4 v[200:201], off
	v_lshl_add_u64 v[200:201], v[230:231], 0, s[64:65]
	s_mov_b32 m0, s6
	s_nop 0
	global_load_lds_dwordx4 v[200:201], off
	v_lshl_add_u64 v[200:201], v[232:233], 0, s[64:65]
	s_add_i32 m0, s6, 0x2000
	s_nop 0
	global_load_lds_dwordx4 v[200:201], off
	v_lshl_add_u64 v[200:201], v[234:235], 0, s[64:65]
	s_mov_b32 m0, s81
	s_nop 0
	global_load_lds_dwordx4 v[200:201], off
	v_lshl_add_u64 v[200:201], v[236:237], 0, s[64:65]
	s_mov_b32 m0, s82
	s_nop 0
	global_load_lds_dwordx4 v[200:201], off
	ds_read_b128 v[160:163], v214 offset:49152
	ds_read_b128 v[164:167], v214 offset:50176
	ds_read_b128 v[168:171], v214 offset:51200
	ds_read_b128 v[172:175], v214 offset:52224
	ds_read_b128 v[196:199], v214 offset:53248
	ds_read_b128 v[216:219], v214 offset:54272
	ds_read_b128 v[220:223], v214 offset:55296
	ds_read_b128 v[224:227], v214 offset:56320
	s_waitcnt vmcnt(8)
	s_waitcnt lgkmcnt(0)
	s_barrier
	s_setprio 1
	s_waitcnt lgkmcnt(0)
	v_mfma_f32_16x16x32_bf16 v[60:63], v[128:131], v[160:163], v[60:63]
	v_mfma_f32_16x16x32_bf16 v[56:59], v[136:139], v[160:163], v[56:59]
	v_mfma_f32_16x16x32_bf16 v[44:47], v[128:131], v[168:171], v[44:47]
	v_mfma_f32_16x16x32_bf16 v[40:43], v[136:139], v[168:171], v[40:43]
	v_mfma_f32_16x16x32_bf16 v[28:31], v[128:131], v[196:199], v[28:31]
	v_mfma_f32_16x16x32_bf16 v[24:27], v[136:139], v[196:199], v[24:27]
	v_mfma_f32_16x16x32_bf16 v[12:15], v[128:131], v[220:223], v[12:15]
	v_mfma_f32_16x16x32_bf16 v[8:11], v[136:139], v[220:223], v[8:11]
	v_mfma_f32_16x16x32_bf16 v[60:63], v[132:135], v[164:167], v[60:63]
	v_mfma_f32_16x16x32_bf16 v[56:59], v[140:143], v[164:167], v[56:59]
	v_mfma_f32_16x16x32_bf16 v[44:47], v[132:135], v[172:175], v[44:47]
	v_mfma_f32_16x16x32_bf16 v[40:43], v[140:143], v[172:175], v[40:43]
	v_mfma_f32_16x16x32_bf16 v[28:31], v[132:135], v[216:219], v[28:31]
	v_mfma_f32_16x16x32_bf16 v[24:27], v[140:143], v[216:219], v[24:27]
	v_mfma_f32_16x16x32_bf16 v[12:15], v[132:135], v[224:227], v[12:15]
	v_mfma_f32_16x16x32_bf16 v[8:11], v[140:143], v[224:227], v[8:11]
	s_setprio 0
	s_setprio 1
	v_mfma_f32_16x16x32_bf16 v[52:55], v[144:147], v[160:163], v[52:55]
	v_mfma_f32_16x16x32_bf16 v[48:51], v[152:155], v[160:163], v[48:51]
	v_mfma_f32_16x16x32_bf16 v[36:39], v[144:147], v[168:171], v[36:39]
	v_mfma_f32_16x16x32_bf16 v[32:35], v[152:155], v[168:171], v[32:35]
	v_mfma_f32_16x16x32_bf16 v[20:23], v[144:147], v[196:199], v[20:23]
	v_mfma_f32_16x16x32_bf16 v[16:19], v[152:155], v[196:199], v[16:19]
	v_mfma_f32_16x16x32_bf16 v[4:7], v[144:147], v[220:223], v[4:7]
	v_mfma_f32_16x16x32_bf16 v[0:3], v[152:155], v[220:223], v[0:3]
	v_mfma_f32_16x16x32_bf16 v[52:55], v[148:151], v[164:167], v[52:55]
	v_mfma_f32_16x16x32_bf16 v[48:51], v[156:159], v[164:167], v[48:51]
	v_mfma_f32_16x16x32_bf16 v[36:39], v[148:151], v[172:175], v[36:39]
	v_mfma_f32_16x16x32_bf16 v[32:35], v[156:159], v[172:175], v[32:35]
	v_mfma_f32_16x16x32_bf16 v[20:23], v[148:151], v[216:219], v[20:23]
	v_mfma_f32_16x16x32_bf16 v[16:19], v[156:159], v[216:219], v[16:19]
	v_mfma_f32_16x16x32_bf16 v[4:7], v[148:151], v[224:227], v[4:7]
	v_mfma_f32_16x16x32_bf16 v[0:3], v[156:159], v[224:227], v[0:3]
	s_setprio 0
	s_barrier
	s_add_u32 s36, s36, 0x100
	s_addc_u32 s37, s37, 0
	s_add_u32 s8, s8, 0x100
	s_addc_u32 s9, s9, 0
	s_cmp_ge_u32 s31, s80
	s_mov_b32 s6, s31
	s_cbranch_scc0 .LBB0_1010
	s_and_b64 vcc, exec, s[40:41]
	s_cbranch_vccz .LBB0_1013
	s_barrier

.LBB0_1084:
	s_add_u32 s2, s0, 0xfffc0080
	s_addc_u32 s3, s1, -1
	s_add_i32 s54, 0, 0x10000
	s_cmp_eq_u32 s37, 12
	s_cselect_b32 s5, s47, s3
	s_cselect_b32 s4, s46, s2
	s_cselect_b32 s3, s49, s36
	s_cselect_b32 s2, s48, s9
	s_add_i32 s58, 0, 0x14000
	v_add_u32_e32 v140, s54, v173
	v_add_u32_e32 v168, s58, v173
	v_lshl_add_u64 v[170:171], s[0:1], 0, v[152:153]
	s_add_i32 m0, s79, 0xc000
	global_load_lds_dwordx4 v[170:171], off
	v_lshl_add_u64 v[170:171], s[0:1], 0, v[154:155]
	s_add_i32 m0, s79, 0xe000
	s_nop 0
	global_load_lds_dwordx4 v[170:171], off
	ds_read_b128 v[128:131], v140
	ds_read_b128 v[132:135], v140 offset:1024
	ds_read_b128 v[136:139], v140 offset:2048
	ds_read_b128 v[140:143], v140 offset:3072
	ds_read_b128 v[156:159], v168
	ds_read_b128 v[160:163], v168 offset:1024
	ds_read_b128 v[164:167], v168 offset:2048
	ds_read_b128 v[184:187], v168 offset:3072
	ds_read_b128 v[188:191], v175
	ds_read_b128 v[192:195], v175 offset:1024
	ds_read_b128 v[196:199], v175 offset:2048
	ds_read_b128 v[214:217], v175 offset:3072
	ds_read_b128 v[218:221], v175 offset:4096
	ds_read_b128 v[222:225], v175 offset:5120
	ds_read_b128 v[226:229], v175 offset:6144
	ds_read_b128 v[230:233], v175 offset:7168
	s_waitcnt vmcnt(8)
	s_waitcnt lgkmcnt(0)
	s_barrier
	s_setprio 1
	s_waitcnt lgkmcnt(0)
	v_mfma_f32_16x16x32_bf16 v[124:127], v[128:131], v[188:191], v[124:127]
	v_mfma_f32_16x16x32_bf16 v[116:119], v[136:139], v[188:191], v[116:119]
	v_mfma_f32_16x16x32_bf16 v[108:111], v[128:131], v[196:199], v[108:111]
	v_mfma_f32_16x16x32_bf16 v[100:103], v[136:139], v[196:199], v[100:103]
	v_mfma_f32_16x16x32_bf16 v[92:95], v[128:131], v[218:221], v[92:95]
	v_mfma_f32_16x16x32_bf16 v[84:87], v[136:139], v[218:221], v[84:87]
	v_mfma_f32_16x16x32_bf16 v[76:79], v[128:131], v[226:229], v[76:79]
	v_mfma_f32_16x16x32_bf16 v[68:71], v[136:139], v[226:229], v[68:71]
	v_mfma_f32_16x16x32_bf16 v[124:127], v[132:135], v[192:195], v[124:127]
	v_mfma_f32_16x16x32_bf16 v[116:119], v[140:143], v[192:195], v[116:119]
	v_mfma_f32_16x16x32_bf16 v[108:111], v[132:135], v[214:217], v[108:111]
	v_mfma_f32_16x16x32_bf16 v[100:103], v[140:143], v[214:217], v[100:103]
	v_mfma_f32_16x16x32_bf16 v[92:95], v[132:135], v[222:225], v[92:95]
	v_mfma_f32_16x16x32_bf16 v[84:87], v[140:143], v[222:225], v[84:87]
	v_mfma_f32_16x16x32_bf16 v[76:79], v[132:135], v[230:233], v[76:79]
	v_mfma_f32_16x16x32_bf16 v[68:71], v[140:143], v[230:233], v[68:71]
	s_setprio 0
	s_setprio 1
	v_mfma_f32_16x16x32_bf16 v[120:123], v[156:159], v[188:191], v[120:123]
	v_mfma_f32_16x16x32_bf16 v[112:115], v[164:167], v[188:191], v[112:115]
	v_mfma_f32_16x16x32_bf16 v[104:107], v[156:159], v[196:199], v[104:107]
	v_mfma_f32_16x16x32_bf16 v[96:99], v[164:167], v[196:199], v[96:99]
	v_mfma_f32_16x16x32_bf16 v[88:91], v[156:159], v[218:221], v[88:91]
	v_mfma_f32_16x16x32_bf16 v[80:83], v[164:167], v[218:221], v[80:83]
	v_mfma_f32_16x16x32_bf16 v[72:75], v[156:159], v[226:229], v[72:75]
	v_mfma_f32_16x16x32_bf16 v[64:67], v[164:167], v[226:229], v[64:67]
	v_mfma_f32_16x16x32_bf16 v[120:123], v[160:163], v[192:195], v[120:123]
	v_mfma_f32_16x16x32_bf16 v[112:115], v[184:187], v[192:195], v[112:115]
	v_mfma_f32_16x16x32_bf16 v[104:107], v[160:163], v[214:217], v[104:107]
	v_mfma_f32_16x16x32_bf16 v[96:99], v[184:187], v[214:217], v[96:99]
	v_mfma_f32_16x16x32_bf16 v[88:91], v[160:163], v[222:225], v[88:91]
	v_mfma_f32_16x16x32_bf16 v[80:83], v[184:187], v[222:225], v[80:83]
	v_mfma_f32_16x16x32_bf16 v[72:75], v[160:163], v[230:233], v[72:75]
	v_mfma_f32_16x16x32_bf16 v[64:67], v[184:187], v[230:233], v[64:67]
	s_setprio 0
	s_barrier
	s_add_i32 s54, s54, s78
	v_lshl_add_u64 v[170:171], s[2:3], 0, v[146:147]
	s_mov_b32 m0, s54
	global_load_lds_dwordx4 v[170:171], off
	s_add_i32 m0, s54, 0x2000
	s_add_u32 s92, s2, 0x40000
	v_lshl_add_u64 v[200:201], s[2:3], 0, v[150:151]
	s_addc_u32 s93, s3, 0
	s_add_i32 s54, s58, s78
	global_load_lds_dwordx4 v[200:201], off
	v_lshl_add_u64 v[234:235], s[92:93], 0, v[146:147]
	s_mov_b32 m0, s54
	v_lshl_add_u64 v[236:237], s[4:5], 0, v[148:149]
	global_load_lds_dwordx4 v[234:235], off
	v_lshl_add_u64 v[234:235], s[92:93], 0, v[150:151]
	s_add_i32 m0, s54, 0x2000
	s_nop 0
	global_load_lds_dwordx4 v[234:235], off
	v_lshl_add_u64 v[234:235], s[4:5], 0, v[144:145]
	s_mov_b32 m0, s79
	s_nop 0
	global_load_lds_dwordx4 v[234:235], off
	s_mov_b32 m0, s80
	s_nop 0
	global_load_lds_dwordx4 v[236:237], off
	ds_read_b128 v[188:191], v175 offset:16384
	ds_read_b128 v[192:195], v175 offset:17408
	ds_read_b128 v[196:199], v175 offset:18432
	ds_read_b128 v[214:217], v175 offset:19456
	ds_read_b128 v[218:221], v175 offset:20480
	ds_read_b128 v[222:225], v175 offset:21504
	ds_read_b128 v[226:229], v175 offset:22528
	ds_read_b128 v[230:233], v175 offset:23552
	s_waitcnt vmcnt(8)
	s_waitcnt lgkmcnt(0)
	s_barrier
	s_setprio 1
	s_waitcnt lgkmcnt(0)
	v_mfma_f32_16x16x32_bf16 v[60:63], v[128:131], v[188:191], v[60:63]
	v_mfma_f32_16x16x32_bf16 v[52:55], v[136:139], v[188:191], v[52:55]
	v_mfma_f32_16x16x32_bf16 v[44:47], v[128:131], v[196:199], v[44:47]
	v_mfma_f32_16x16x32_bf16 v[36:39], v[136:139], v[196:199], v[36:39]
	v_mfma_f32_16x16x32_bf16 v[28:31], v[128:131], v[218:221], v[28:31]
	v_mfma_f32_16x16x32_bf16 v[20:23], v[136:139], v[218:221], v[20:23]
	v_mfma_f32_16x16x32_bf16 v[12:15], v[128:131], v[226:229], v[12:15]
	v_mfma_f32_16x16x32_bf16 v[4:7], v[136:139], v[226:229], v[4:7]
	v_mfma_f32_16x16x32_bf16 v[60:63], v[132:135], v[192:195], v[60:63]
	v_mfma_f32_16x16x32_bf16 v[52:55], v[140:143], v[192:195], v[52:55]
	v_mfma_f32_16x16x32_bf16 v[44:47], v[132:135], v[214:217], v[44:47]
	v_mfma_f32_16x16x32_bf16 v[36:39], v[140:143], v[214:217], v[36:39]
	v_mfma_f32_16x16x32_bf16 v[28:31], v[132:135], v[222:225], v[28:31]
	v_mfma_f32_16x16x32_bf16 v[20:23], v[140:143], v[222:225], v[20:23]
	v_mfma_f32_16x16x32_bf16 v[12:15], v[132:135], v[230:233], v[12:15]
	v_mfma_f32_16x16x32_bf16 v[4:7], v[140:143], v[230:233], v[4:7]
	s_setprio 0
	s_setprio 1
	v_mfma_f32_16x16x32_bf16 v[56:59], v[156:159], v[188:191], v[56:59]
	v_mfma_f32_16x16x32_bf16 v[48:51], v[164:167], v[188:191], v[48:51]
	v_mfma_f32_16x16x32_bf16 v[40:43], v[156:159], v[196:199], v[40:43]
	v_mfma_f32_16x16x32_bf16 v[32:35], v[164:167], v[196:199], v[32:35]
	v_mfma_f32_16x16x32_bf16 v[24:27], v[156:159], v[218:221], v[24:27]
	v_mfma_f32_16x16x32_bf16 v[16:19], v[164:167], v[218:221], v[16:19]
	v_mfma_f32_16x16x32_bf16 v[8:11], v[156:159], v[226:229], v[8:11]
	v_mfma_f32_16x16x32_bf16 v[0:3], v[164:167], v[226:229], v[0:3]
	v_mfma_f32_16x16x32_bf16 v[56:59], v[160:163], v[192:195], v[56:59]
	v_mfma_f32_16x16x32_bf16 v[48:51], v[184:187], v[192:195], v[48:51]
	v_mfma_f32_16x16x32_bf16 v[40:43], v[160:163], v[214:217], v[40:43]
	v_mfma_f32_16x16x32_bf16 v[32:35], v[184:187], v[214:217], v[32:35]
	v_mfma_f32_16x16x32_bf16 v[24:27], v[160:163], v[222:225], v[24:27]
	v_mfma_f32_16x16x32_bf16 v[16:19], v[184:187], v[222:225], v[16:19]
	v_mfma_f32_16x16x32_bf16 v[8:11], v[160:163], v[230:233], v[8:11]
	v_mfma_f32_16x16x32_bf16 v[0:3], v[184:187], v[230:233], v[0:3]
	s_setprio 0
	s_barrier
	s_add_i32 s54, 0, 0x18000
	s_add_i32 s58, 0, 0x1c000
	v_add_u32_e32 v140, s54, v173
	v_add_u32_e32 v168, s58, v173
	s_add_u32 s4, s4, 0x40000
	s_addc_u32 s5, s5, 0
	s_mov_b32 m0, s81
	v_lshl_add_u64 v[238:239], s[4:5], 0, v[144:145]
	global_load_lds_dwordx4 v[238:239], off
	v_lshl_add_u64 v[238:239], s[4:5], 0, v[148:149]
	s_mov_b32 m0, s82
	s_nop 0
	global_load_lds_dwordx4 v[238:239], off
	ds_read_b128 v[128:131], v140
	ds_read_b128 v[132:135], v140 offset:1024
	ds_read_b128 v[136:139], v140 offset:2048
	ds_read_b128 v[140:143], v140 offset:3072
	ds_read_b128 v[156:159], v168
	ds_read_b128 v[160:163], v168 offset:1024
	ds_read_b128 v[164:167], v168 offset:2048
	ds_read_b128 v[184:187], v168 offset:3072
	ds_read_b128 v[188:191], v175 offset:32768
	ds_read_b128 v[192:195], v175 offset:33792
	ds_read_b128 v[196:199], v175 offset:34816
	ds_read_b128 v[214:217], v175 offset:35840
	ds_read_b128 v[218:221], v175 offset:36864
	ds_read_b128 v[222:225], v175 offset:37888
	ds_read_b128 v[226:229], v175 offset:38912
	ds_read_b128 v[230:233], v175 offset:39936
	s_waitcnt vmcnt(8)
	s_waitcnt lgkmcnt(0)
	s_barrier
	s_setprio 1
	s_waitcnt lgkmcnt(0)
	v_mfma_f32_16x16x32_bf16 v[124:127], v[128:131], v[188:191], v[124:127]
	v_mfma_f32_16x16x32_bf16 v[116:119], v[136:139], v[188:191], v[116:119]
	v_mfma_f32_16x16x32_bf16 v[108:111], v[128:131], v[196:199], v[108:111]
	v_mfma_f32_16x16x32_bf16 v[100:103], v[136:139], v[196:199], v[100:103]
	v_mfma_f32_16x16x32_bf16 v[92:95], v[128:131], v[218:221], v[92:95]
	v_mfma_f32_16x16x32_bf16 v[84:87], v[136:139], v[218:221], v[84:87]
	v_mfma_f32_16x16x32_bf16 v[76:79], v[128:131], v[226:229], v[76:79]
	v_mfma_f32_16x16x32_bf16 v[68:71], v[136:139], v[226:229], v[68:71]
	v_mfma_f32_16x16x32_bf16 v[124:127], v[132:135], v[192:195], v[124:127]
	v_mfma_f32_16x16x32_bf16 v[116:119], v[140:143], v[192:195], v[116:119]
	v_mfma_f32_16x16x32_bf16 v[108:111], v[132:135], v[214:217], v[108:111]
	v_mfma_f32_16x16x32_bf16 v[100:103], v[140:143], v[214:217], v[100:103]
	v_mfma_f32_16x16x32_bf16 v[92:95], v[132:135], v[222:225], v[92:95]
	v_mfma_f32_16x16x32_bf16 v[84:87], v[140:143], v[222:225], v[84:87]
	v_mfma_f32_16x16x32_bf16 v[76:79], v[132:135], v[230:233], v[76:79]
	v_mfma_f32_16x16x32_bf16 v[68:71], v[140:143], v[230:233], v[68:71]
	s_setprio 0
	s_setprio 1
	v_mfma_f32_16x16x32_bf16 v[120:123], v[156:159], v[188:191], v[120:123]
	v_mfma_f32_16x16x32_bf16 v[112:115], v[164:167], v[188:191], v[112:115]
	v_mfma_f32_16x16x32_bf16 v[104:107], v[156:159], v[196:199], v[104:107]
	v_mfma_f32_16x16x32_bf16 v[96:99], v[164:167], v[196:199], v[96:99]
	v_mfma_f32_16x16x32_bf16 v[88:91], v[156:159], v[218:221], v[88:91]
	v_mfma_f32_16x16x32_bf16 v[80:83], v[164:167], v[218:221], v[80:83]
	v_mfma_f32_16x16x32_bf16 v[72:75], v[156:159], v[226:229], v[72:75]
	v_mfma_f32_16x16x32_bf16 v[64:67], v[164:167], v[226:229], v[64:67]
	v_mfma_f32_16x16x32_bf16 v[120:123], v[160:163], v[192:195], v[120:123]
	v_mfma_f32_16x16x32_bf16 v[112:115], v[184:187], v[192:195], v[112:115]
	v_mfma_f32_16x16x32_bf16 v[104:107], v[160:163], v[214:217], v[104:107]
	v_mfma_f32_16x16x32_bf16 v[96:99], v[184:187], v[214:217], v[96:99]
	v_mfma_f32_16x16x32_bf16 v[88:91], v[160:163], v[222:225], v[88:91]
	v_mfma_f32_16x16x32_bf16 v[80:83], v[184:187], v[222:225], v[80:83]
	v_mfma_f32_16x16x32_bf16 v[72:75], v[160:163], v[230:233], v[72:75]
	v_mfma_f32_16x16x32_bf16 v[64:67], v[184:187], v[230:233], v[64:67]
	s_setprio 0
	s_barrier
	s_add_i32 s4, s54, s78
	v_lshl_add_u64 v[170:171], v[170:171], 0, s[64:65]
	s_mov_b32 m0, s4
	global_load_lds_dwordx4 v[170:171], off
	s_add_i32 m0, s4, 0x2000
	s_add_u32 s2, s2, 0x40080
	v_lshl_add_u64 v[170:171], v[200:201], 0, s[64:65]
	s_addc_u32 s3, s3, 0
	s_add_i32 s4, s58, s78
	global_load_lds_dwordx4 v[170:171], off
	v_lshl_add_u64 v[170:171], s[2:3], 0, v[146:147]
	s_mov_b32 m0, s4
	s_nop 0
	global_load_lds_dwordx4 v[170:171], off
	v_lshl_add_u64 v[170:171], s[2:3], 0, v[150:151]
	s_add_i32 m0, s4, 0x2000
	s_nop 0
	global_load_lds_dwordx4 v[170:171], off
	v_lshl_add_u64 v[170:171], v[234:235], 0, s[64:65]
	s_mov_b32 m0, s83
	s_nop 0
	global_load_lds_dwordx4 v[170:171], off
	v_lshl_add_u64 v[170:171], v[236:237], 0, s[64:65]
	s_mov_b32 m0, s84
	s_nop 0
	global_load_lds_dwordx4 v[170:171], off
	ds_read_b128 v[188:191], v175 offset:49152
	ds_read_b128 v[192:195], v175 offset:50176
	ds_read_b128 v[196:199], v175 offset:51200
	ds_read_b128 v[214:217], v175 offset:52224
	ds_read_b128 v[218:221], v175 offset:53248
	ds_read_b128 v[222:225], v175 offset:54272
	ds_read_b128 v[226:229], v175 offset:55296
	ds_read_b128 v[230:233], v175 offset:56320
	s_waitcnt vmcnt(8)
	s_waitcnt lgkmcnt(0)
	s_barrier
	s_setprio 1
	s_waitcnt lgkmcnt(0)
	v_mfma_f32_16x16x32_bf16 v[60:63], v[128:131], v[188:191], v[60:63]
	v_mfma_f32_16x16x32_bf16 v[52:55], v[136:139], v[188:191], v[52:55]
	v_mfma_f32_16x16x32_bf16 v[44:47], v[128:131], v[196:199], v[44:47]
	v_mfma_f32_16x16x32_bf16 v[36:39], v[136:139], v[196:199], v[36:39]
	v_mfma_f32_16x16x32_bf16 v[28:31], v[128:131], v[218:221], v[28:31]
	v_mfma_f32_16x16x32_bf16 v[20:23], v[136:139], v[218:221], v[20:23]
	v_mfma_f32_16x16x32_bf16 v[12:15], v[128:131], v[226:229], v[12:15]
	v_mfma_f32_16x16x32_bf16 v[4:7], v[136:139], v[226:229], v[4:7]
	v_mfma_f32_16x16x32_bf16 v[60:63], v[132:135], v[192:195], v[60:63]
	v_mfma_f32_16x16x32_bf16 v[52:55], v[140:143], v[192:195], v[52:55]
	v_mfma_f32_16x16x32_bf16 v[44:47], v[132:135], v[214:217], v[44:47]
	v_mfma_f32_16x16x32_bf16 v[36:39], v[140:143], v[214:217], v[36:39]
	v_mfma_f32_16x16x32_bf16 v[28:31], v[132:135], v[222:225], v[28:31]
	v_mfma_f32_16x16x32_bf16 v[20:23], v[140:143], v[222:225], v[20:23]
	v_mfma_f32_16x16x32_bf16 v[12:15], v[132:135], v[230:233], v[12:15]
	v_mfma_f32_16x16x32_bf16 v[4:7], v[140:143], v[230:233], v[4:7]
	s_setprio 0
	s_setprio 1
	v_mfma_f32_16x16x32_bf16 v[56:59], v[156:159], v[188:191], v[56:59]
	v_mfma_f32_16x16x32_bf16 v[48:51], v[164:167], v[188:191], v[48:51]
	v_mfma_f32_16x16x32_bf16 v[40:43], v[156:159], v[196:199], v[40:43]
	v_mfma_f32_16x16x32_bf16 v[32:35], v[164:167], v[196:199], v[32:35]
	v_mfma_f32_16x16x32_bf16 v[24:27], v[156:159], v[218:221], v[24:27]
	v_mfma_f32_16x16x32_bf16 v[16:19], v[164:167], v[218:221], v[16:19]
	v_mfma_f32_16x16x32_bf16 v[8:11], v[156:159], v[226:229], v[8:11]
	v_mfma_f32_16x16x32_bf16 v[0:3], v[164:167], v[226:229], v[0:3]
	v_mfma_f32_16x16x32_bf16 v[56:59], v[160:163], v[192:195], v[56:59]
	v_mfma_f32_16x16x32_bf16 v[48:51], v[184:187], v[192:195], v[48:51]
	v_mfma_f32_16x16x32_bf16 v[40:43], v[160:163], v[214:217], v[40:43]
	v_mfma_f32_16x16x32_bf16 v[32:35], v[184:187], v[214:217], v[32:35]
	v_mfma_f32_16x16x32_bf16 v[24:27], v[160:163], v[222:225], v[24:27]
	v_mfma_f32_16x16x32_bf16 v[16:19], v[184:187], v[222:225], v[16:19]
	v_mfma_f32_16x16x32_bf16 v[8:11], v[160:163], v[230:233], v[8:11]
	v_mfma_f32_16x16x32_bf16 v[0:3], v[184:187], v[230:233], v[0:3]
	s_setprio 0
	s_barrier
	s_add_i32 s37, s37, 2
	s_add_u32 s0, s0, 0x100
	s_addc_u32 s1, s1, 0
	s_add_u32 s9, s9, 0x100
	s_addc_u32 s36, s36, 0
	s_cmp_gt_u32 s37, 13
	s_cbranch_scc0 .LBB0_1084
	s_and_b64 vcc, exec, s[44:45]
	s_cbranch_vccz .LBB0_1087
	s_barrier

.LBB0_1137:
	s_add_i32 s47, s42, 2
	s_add_u32 s58, s44, 0x80
	s_addc_u32 s43, s45, 0
	s_add_i32 s59, 0, 0x10000
	s_cmp_eq_u32 s85, s42
	s_cselect_b32 s43, s39, s43
	s_cselect_b32 s42, s38, s58
	v_add_u32_e32 v141, s59, v139
	s_cselect_b32 s93, s41, s46
	s_cselect_b32 s92, s40, s25
	s_add_i32 s58, 0, 0x14000
	ds_read_b128 v[142:145], v141
	ds_read_b128 v[146:149], v141 offset:1024
	ds_read_b128 v[150:153], v141 offset:2048
	ds_read_b128 v[154:157], v141 offset:3072
	v_add_u32_e32 v141, s58, v139
	ds_read_b128 v[158:161], v141
	ds_read_b128 v[162:165], v141 offset:1024
	ds_read_b128 v[166:169], v141 offset:2048
	ds_read_b128 v[170:173], v141 offset:3072
	v_lshl_add_u64 v[174:175], s[44:45], 0, v[134:135]
	s_add_i32 m0, s9, 0xc000
	ds_read_b128 v[184:187], v140
	ds_read_b128 v[188:191], v140 offset:1024
	ds_read_b128 v[192:195], v140 offset:2048
	ds_read_b128 v[196:199], v140 offset:3072
	ds_read_b128 v[214:217], v140 offset:4096
	ds_read_b128 v[218:221], v140 offset:5120
	ds_read_b128 v[222:225], v140 offset:6144
	ds_read_b128 v[226:229], v140 offset:7168
	global_load_lds_dwordx4 v[174:175], off
	v_lshl_add_u64 v[174:175], s[44:45], 0, v[136:137]
	s_add_i32 m0, s9, 0xe000
	s_nop 0
	global_load_lds_dwordx4 v[174:175], off
	s_waitcnt vmcnt(8)
	s_waitcnt lgkmcnt(0)
	s_barrier
	s_setprio 1
	s_waitcnt lgkmcnt(0)
	v_mfma_f32_16x16x32_bf16 v[124:127], v[142:145], v[184:187], v[124:127]
	v_mfma_f32_16x16x32_bf16 v[120:123], v[150:153], v[184:187], v[120:123]
	v_mfma_f32_16x16x32_bf16 v[116:119], v[142:145], v[192:195], v[116:119]
	v_mfma_f32_16x16x32_bf16 v[108:111], v[150:153], v[192:195], v[108:111]
	v_mfma_f32_16x16x32_bf16 v[100:103], v[142:145], v[214:217], v[100:103]
	v_mfma_f32_16x16x32_bf16 v[92:95], v[150:153], v[214:217], v[92:95]
	v_mfma_f32_16x16x32_bf16 v[84:87], v[142:145], v[222:225], v[84:87]
	v_mfma_f32_16x16x32_bf16 v[76:79], v[150:153], v[222:225], v[76:79]
	v_mfma_f32_16x16x32_bf16 v[124:127], v[146:149], v[188:191], v[124:127]
	v_mfma_f32_16x16x32_bf16 v[120:123], v[154:157], v[188:191], v[120:123]
	v_mfma_f32_16x16x32_bf16 v[116:119], v[146:149], v[196:199], v[116:119]
	v_mfma_f32_16x16x32_bf16 v[108:111], v[154:157], v[196:199], v[108:111]
	v_mfma_f32_16x16x32_bf16 v[100:103], v[146:149], v[218:221], v[100:103]
	v_mfma_f32_16x16x32_bf16 v[92:95], v[154:157], v[218:221], v[92:95]
	v_mfma_f32_16x16x32_bf16 v[84:87], v[146:149], v[226:229], v[84:87]
	v_mfma_f32_16x16x32_bf16 v[76:79], v[154:157], v[226:229], v[76:79]
	s_setprio 0
	s_setprio 1
	v_mfma_f32_16x16x32_bf16 v[112:115], v[158:161], v[184:187], v[112:115]
	v_mfma_f32_16x16x32_bf16 v[104:107], v[166:169], v[184:187], v[104:107]
	v_mfma_f32_16x16x32_bf16 v[96:99], v[158:161], v[192:195], v[96:99]
	v_mfma_f32_16x16x32_bf16 v[88:91], v[166:169], v[192:195], v[88:91]
	v_mfma_f32_16x16x32_bf16 v[80:83], v[158:161], v[214:217], v[80:83]
	v_mfma_f32_16x16x32_bf16 v[72:75], v[166:169], v[214:217], v[72:75]
	v_mfma_f32_16x16x32_bf16 v[68:71], v[158:161], v[222:225], v[68:71]
	v_mfma_f32_16x16x32_bf16 v[64:67], v[166:169], v[222:225], v[64:67]
	v_mfma_f32_16x16x32_bf16 v[112:115], v[162:165], v[188:191], v[112:115]
	v_mfma_f32_16x16x32_bf16 v[104:107], v[170:173], v[188:191], v[104:107]
	v_mfma_f32_16x16x32_bf16 v[96:99], v[162:165], v[196:199], v[96:99]
	v_mfma_f32_16x16x32_bf16 v[88:91], v[170:173], v[196:199], v[88:91]
	v_mfma_f32_16x16x32_bf16 v[80:83], v[162:165], v[218:221], v[80:83]
	v_mfma_f32_16x16x32_bf16 v[72:75], v[170:173], v[218:221], v[72:75]
	v_mfma_f32_16x16x32_bf16 v[68:71], v[162:165], v[226:229], v[68:71]
	v_mfma_f32_16x16x32_bf16 v[64:67], v[170:173], v[226:229], v[64:67]
	s_setprio 0
	s_barrier
	s_add_i32 s59, s59, s8
	v_lshl_add_u64 v[174:175], s[92:93], 0, v[176:177]
	s_mov_b32 m0, s59
	global_load_lds_dwordx4 v[174:175], off
	s_add_i32 m0, s59, 0x2000
	v_lshl_add_u64 v[200:201], s[92:93], 0, v[132:133]
	s_add_u32 s92, s92, s20
	s_addc_u32 s93, s93, s21
	s_add_i32 s58, s58, s8
	global_load_lds_dwordx4 v[200:201], off
	v_lshl_add_u64 v[230:231], s[92:93], 0, v[176:177]
	s_mov_b32 m0, s58
	v_lshl_add_u64 v[232:233], s[92:93], 0, v[132:133]
	global_load_lds_dwordx4 v[230:231], off
	s_add_i32 m0, s58, 0x2000
	v_lshl_add_u64 v[234:235], s[42:43], 0, v[128:129]
	global_load_lds_dwordx4 v[232:233], off
	s_mov_b32 m0, s9
	v_lshl_add_u64 v[236:237], s[42:43], 0, v[130:131]
	global_load_lds_dwordx4 v[234:235], off
	s_mov_b32 m0, s78
	s_nop 0
	global_load_lds_dwordx4 v[236:237], off
	ds_read_b128 v[184:187], v140 offset:16384
	ds_read_b128 v[188:191], v140 offset:17408
	ds_read_b128 v[192:195], v140 offset:18432
	ds_read_b128 v[196:199], v140 offset:19456
	ds_read_b128 v[214:217], v140 offset:20480
	ds_read_b128 v[218:221], v140 offset:21504
	ds_read_b128 v[222:225], v140 offset:22528
	ds_read_b128 v[226:229], v140 offset:23552
	s_waitcnt vmcnt(8)
	s_waitcnt lgkmcnt(0)
	s_barrier
	s_setprio 1
	s_waitcnt lgkmcnt(0)
	v_mfma_f32_16x16x32_bf16 v[60:63], v[142:145], v[184:187], v[60:63]
	v_mfma_f32_16x16x32_bf16 v[56:59], v[150:153], v[184:187], v[56:59]
	v_mfma_f32_16x16x32_bf16 v[52:55], v[142:145], v[192:195], v[52:55]
	v_mfma_f32_16x16x32_bf16 v[44:47], v[150:153], v[192:195], v[44:47]
	v_mfma_f32_16x16x32_bf16 v[36:39], v[142:145], v[214:217], v[36:39]
	v_mfma_f32_16x16x32_bf16 v[28:31], v[150:153], v[214:217], v[28:31]
	v_mfma_f32_16x16x32_bf16 v[20:23], v[142:145], v[222:225], v[20:23]
	v_mfma_f32_16x16x32_bf16 v[12:15], v[150:153], v[222:225], v[12:15]
	v_mfma_f32_16x16x32_bf16 v[60:63], v[146:149], v[188:191], v[60:63]
	v_mfma_f32_16x16x32_bf16 v[56:59], v[154:157], v[188:191], v[56:59]
	v_mfma_f32_16x16x32_bf16 v[52:55], v[146:149], v[196:199], v[52:55]
	v_mfma_f32_16x16x32_bf16 v[44:47], v[154:157], v[196:199], v[44:47]
	v_mfma_f32_16x16x32_bf16 v[36:39], v[146:149], v[218:221], v[36:39]
	v_mfma_f32_16x16x32_bf16 v[28:31], v[154:157], v[218:221], v[28:31]
	v_mfma_f32_16x16x32_bf16 v[20:23], v[146:149], v[226:229], v[20:23]
	v_mfma_f32_16x16x32_bf16 v[12:15], v[154:157], v[226:229], v[12:15]
	s_setprio 0
	s_setprio 1
	v_mfma_f32_16x16x32_bf16 v[48:51], v[158:161], v[184:187], v[48:51]
	v_mfma_f32_16x16x32_bf16 v[40:43], v[166:169], v[184:187], v[40:43]
	v_mfma_f32_16x16x32_bf16 v[32:35], v[158:161], v[192:195], v[32:35]
	v_mfma_f32_16x16x32_bf16 v[24:27], v[166:169], v[192:195], v[24:27]
	v_mfma_f32_16x16x32_bf16 v[16:19], v[158:161], v[214:217], v[16:19]
	v_mfma_f32_16x16x32_bf16 v[8:11], v[166:169], v[214:217], v[8:11]
	v_mfma_f32_16x16x32_bf16 v[4:7], v[158:161], v[222:225], v[4:7]
	v_mfma_f32_16x16x32_bf16 v[0:3], v[166:169], v[222:225], v[0:3]
	v_mfma_f32_16x16x32_bf16 v[48:51], v[162:165], v[188:191], v[48:51]
	v_mfma_f32_16x16x32_bf16 v[40:43], v[170:173], v[188:191], v[40:43]
	v_mfma_f32_16x16x32_bf16 v[32:35], v[162:165], v[196:199], v[32:35]
	v_mfma_f32_16x16x32_bf16 v[24:27], v[170:173], v[196:199], v[24:27]
	v_mfma_f32_16x16x32_bf16 v[16:19], v[162:165], v[218:221], v[16:19]
	v_mfma_f32_16x16x32_bf16 v[8:11], v[170:173], v[218:221], v[8:11]
	v_mfma_f32_16x16x32_bf16 v[4:7], v[162:165], v[226:229], v[4:7]
	v_mfma_f32_16x16x32_bf16 v[0:3], v[170:173], v[226:229], v[0:3]
	s_setprio 0
	s_barrier
	s_add_i32 s58, 0, 0x18000
	v_add_u32_e32 v141, s58, v139
	s_add_i32 s59, 0, 0x1c000
	ds_read_b128 v[142:145], v141
	ds_read_b128 v[146:149], v141 offset:1024
	ds_read_b128 v[150:153], v141 offset:2048
	ds_read_b128 v[154:157], v141 offset:3072
	v_add_u32_e32 v141, s59, v139
	ds_read_b128 v[158:161], v141
	ds_read_b128 v[162:165], v141 offset:1024
	ds_read_b128 v[166:169], v141 offset:2048
	ds_read_b128 v[170:173], v141 offset:3072
	s_add_u32 s42, s42, s22
	s_addc_u32 s43, s43, s23
	s_mov_b32 m0, s79
	v_lshl_add_u64 v[238:239], s[42:43], 0, v[128:129]
	ds_read_b128 v[184:187], v140 offset:32768
	ds_read_b128 v[188:191], v140 offset:33792
	ds_read_b128 v[192:195], v140 offset:34816
	ds_read_b128 v[196:199], v140 offset:35840
	ds_read_b128 v[214:217], v140 offset:36864
	ds_read_b128 v[218:221], v140 offset:37888
	ds_read_b128 v[222:225], v140 offset:38912
	ds_read_b128 v[226:229], v140 offset:39936
	global_load_lds_dwordx4 v[238:239], off
	v_lshl_add_u64 v[238:239], s[42:43], 0, v[130:131]
	s_mov_b32 m0, s80
	s_nop 0
	global_load_lds_dwordx4 v[238:239], off
	s_waitcnt vmcnt(8)
	s_waitcnt lgkmcnt(0)
	s_barrier
	s_setprio 1
	s_waitcnt lgkmcnt(0)
	v_mfma_f32_16x16x32_bf16 v[124:127], v[142:145], v[184:187], v[124:127]
	v_mfma_f32_16x16x32_bf16 v[120:123], v[150:153], v[184:187], v[120:123]
	v_mfma_f32_16x16x32_bf16 v[116:119], v[142:145], v[192:195], v[116:119]
	v_mfma_f32_16x16x32_bf16 v[108:111], v[150:153], v[192:195], v[108:111]
	v_mfma_f32_16x16x32_bf16 v[100:103], v[142:145], v[214:217], v[100:103]
	v_mfma_f32_16x16x32_bf16 v[92:95], v[150:153], v[214:217], v[92:95]
	v_mfma_f32_16x16x32_bf16 v[84:87], v[142:145], v[222:225], v[84:87]
	v_mfma_f32_16x16x32_bf16 v[76:79], v[150:153], v[222:225], v[76:79]
	v_mfma_f32_16x16x32_bf16 v[124:127], v[146:149], v[188:191], v[124:127]
	v_mfma_f32_16x16x32_bf16 v[120:123], v[154:157], v[188:191], v[120:123]
	v_mfma_f32_16x16x32_bf16 v[116:119], v[146:149], v[196:199], v[116:119]
	v_mfma_f32_16x16x32_bf16 v[108:111], v[154:157], v[196:199], v[108:111]
	v_mfma_f32_16x16x32_bf16 v[100:103], v[146:149], v[218:221], v[100:103]
	v_mfma_f32_16x16x32_bf16 v[92:95], v[154:157], v[218:221], v[92:95]
	v_mfma_f32_16x16x32_bf16 v[84:87], v[146:149], v[226:229], v[84:87]
	v_mfma_f32_16x16x32_bf16 v[76:79], v[154:157], v[226:229], v[76:79]
	s_setprio 0
	s_setprio 1
	v_mfma_f32_16x16x32_bf16 v[112:115], v[158:161], v[184:187], v[112:115]
	v_mfma_f32_16x16x32_bf16 v[104:107], v[166:169], v[184:187], v[104:107]
	v_mfma_f32_16x16x32_bf16 v[96:99], v[158:161], v[192:195], v[96:99]
	v_mfma_f32_16x16x32_bf16 v[88:91], v[166:169], v[192:195], v[88:91]
	v_mfma_f32_16x16x32_bf16 v[80:83], v[158:161], v[214:217], v[80:83]
	v_mfma_f32_16x16x32_bf16 v[72:75], v[166:169], v[214:217], v[72:75]
	v_mfma_f32_16x16x32_bf16 v[68:71], v[158:161], v[222:225], v[68:71]
	v_mfma_f32_16x16x32_bf16 v[64:67], v[166:169], v[222:225], v[64:67]
	v_mfma_f32_16x16x32_bf16 v[112:115], v[162:165], v[188:191], v[112:115]
	v_mfma_f32_16x16x32_bf16 v[104:107], v[170:173], v[188:191], v[104:107]
	v_mfma_f32_16x16x32_bf16 v[96:99], v[162:165], v[196:199], v[96:99]
	v_mfma_f32_16x16x32_bf16 v[88:91], v[170:173], v[196:199], v[88:91]
	v_mfma_f32_16x16x32_bf16 v[80:83], v[162:165], v[218:221], v[80:83]
	v_mfma_f32_16x16x32_bf16 v[72:75], v[170:173], v[218:221], v[72:75]
	v_mfma_f32_16x16x32_bf16 v[68:71], v[162:165], v[226:229], v[68:71]
	v_mfma_f32_16x16x32_bf16 v[64:67], v[170:173], v[226:229], v[64:67]
	s_setprio 0
	s_barrier
	s_add_i32 s42, s58, s8
	v_lshl_add_u64 v[174:175], v[174:175], 0, s[10:11]
	s_mov_b32 m0, s42
	global_load_lds_dwordx4 v[174:175], off
	v_lshl_add_u64 v[174:175], v[200:201], 0, s[10:11]
	s_add_i32 m0, s42, 0x2000
	s_add_i32 s42, s59, s8
	global_load_lds_dwordx4 v[174:175], off
	v_lshl_add_u64 v[174:175], v[230:231], 0, s[10:11]
	s_mov_b32 m0, s42
	s_nop 0
	global_load_lds_dwordx4 v[174:175], off
	v_lshl_add_u64 v[174:175], v[232:233], 0, s[10:11]
	s_add_i32 m0, s42, 0x2000
	s_nop 0
	global_load_lds_dwordx4 v[174:175], off
	v_lshl_add_u64 v[174:175], v[234:235], 0, s[10:11]
	s_mov_b32 m0, s83
	s_nop 0
	global_load_lds_dwordx4 v[174:175], off
	v_lshl_add_u64 v[174:175], v[236:237], 0, s[10:11]
	s_mov_b32 m0, s84
	s_nop 0
	global_load_lds_dwordx4 v[174:175], off
	ds_read_b128 v[184:187], v140 offset:49152
	ds_read_b128 v[188:191], v140 offset:50176
	ds_read_b128 v[192:195], v140 offset:51200
	ds_read_b128 v[196:199], v140 offset:52224
	ds_read_b128 v[214:217], v140 offset:53248
	ds_read_b128 v[218:221], v140 offset:54272
	ds_read_b128 v[222:225], v140 offset:55296
	ds_read_b128 v[226:229], v140 offset:56320
	s_waitcnt vmcnt(8)
	s_waitcnt lgkmcnt(0)
	s_barrier
	s_setprio 1
	s_waitcnt lgkmcnt(0)
	v_mfma_f32_16x16x32_bf16 v[60:63], v[142:145], v[184:187], v[60:63]
	v_mfma_f32_16x16x32_bf16 v[56:59], v[150:153], v[184:187], v[56:59]
	v_mfma_f32_16x16x32_bf16 v[52:55], v[142:145], v[192:195], v[52:55]
	v_mfma_f32_16x16x32_bf16 v[44:47], v[150:153], v[192:195], v[44:47]
	v_mfma_f32_16x16x32_bf16 v[36:39], v[142:145], v[214:217], v[36:39]
	v_mfma_f32_16x16x32_bf16 v[28:31], v[150:153], v[214:217], v[28:31]
	v_mfma_f32_16x16x32_bf16 v[20:23], v[142:145], v[222:225], v[20:23]
	v_mfma_f32_16x16x32_bf16 v[12:15], v[150:153], v[222:225], v[12:15]
	v_mfma_f32_16x16x32_bf16 v[60:63], v[146:149], v[188:191], v[60:63]
	v_mfma_f32_16x16x32_bf16 v[56:59], v[154:157], v[188:191], v[56:59]
	v_mfma_f32_16x16x32_bf16 v[52:55], v[146:149], v[196:199], v[52:55]
	v_mfma_f32_16x16x32_bf16 v[44:47], v[154:157], v[196:199], v[44:47]
	v_mfma_f32_16x16x32_bf16 v[36:39], v[146:149], v[218:221], v[36:39]
	v_mfma_f32_16x16x32_bf16 v[28:31], v[154:157], v[218:221], v[28:31]
	v_mfma_f32_16x16x32_bf16 v[20:23], v[146:149], v[226:229], v[20:23]
	v_mfma_f32_16x16x32_bf16 v[12:15], v[154:157], v[226:229], v[12:15]
	s_setprio 0
	s_setprio 1
	v_mfma_f32_16x16x32_bf16 v[48:51], v[158:161], v[184:187], v[48:51]
	v_mfma_f32_16x16x32_bf16 v[40:43], v[166:169], v[184:187], v[40:43]
	v_mfma_f32_16x16x32_bf16 v[32:35], v[158:161], v[192:195], v[32:35]
	v_mfma_f32_16x16x32_bf16 v[24:27], v[166:169], v[192:195], v[24:27]
	v_mfma_f32_16x16x32_bf16 v[16:19], v[158:161], v[214:217], v[16:19]
	v_mfma_f32_16x16x32_bf16 v[8:11], v[166:169], v[214:217], v[8:11]
	v_mfma_f32_16x16x32_bf16 v[4:7], v[158:161], v[222:225], v[4:7]
	v_mfma_f32_16x16x32_bf16 v[0:3], v[166:169], v[222:225], v[0:3]
	v_mfma_f32_16x16x32_bf16 v[48:51], v[162:165], v[188:191], v[48:51]
	v_mfma_f32_16x16x32_bf16 v[40:43], v[170:173], v[188:191], v[40:43]
	v_mfma_f32_16x16x32_bf16 v[32:35], v[162:165], v[196:199], v[32:35]
	v_mfma_f32_16x16x32_bf16 v[24:27], v[170:173], v[196:199], v[24:27]
	v_mfma_f32_16x16x32_bf16 v[16:19], v[162:165], v[218:221], v[16:19]
	v_mfma_f32_16x16x32_bf16 v[8:11], v[170:173], v[218:221], v[8:11]
	v_mfma_f32_16x16x32_bf16 v[4:7], v[162:165], v[226:229], v[4:7]
	v_mfma_f32_16x16x32_bf16 v[0:3], v[170:173], v[226:229], v[0:3]
	s_setprio 0
	s_barrier
	s_add_u32 s44, s44, 0x100
	s_addc_u32 s45, s45, 0
	s_add_u32 s25, s25, 0x100
	s_addc_u32 s46, s46, 0
	s_cmp_ge_u32 s47, s77
	s_mov_b32 s42, s47
	s_cbranch_scc0 .LBB0_1137
	s_and_b64 vcc, exec, s[34:35]
	s_cbranch_vccz .LBB0_1140
	s_barrier
